# a27 + mla_prep LDS staging made bank-conflict free: per-lane slot pitch 192->208 B (AQ/AK) and 128->144 B (AV), 16 KB per wave
# speedup vs baseline: 1.0017x; 1.0015x over previous
.LBB0_535:
	v_ashrrev_i32_e32 v111, 31, v110
	v_lshlrev_b64 v[0:1], 9, v[110:111]
	v_lshl_add_u64 v[0:1], v[106:107], 0, v[0:1]
	global_load_dwordx4 v[24:27], v[0:1], off
	global_load_dwordx4 v[28:31], v[0:1], off offset:16
	global_load_dwordx4 v[36:39], v[0:1], off offset:32
	global_load_dwordx4 v[40:43], v[0:1], off offset:48
	v_ashrrev_i32_e32 v2, 10, v110
	v_and_or_b32 v60, v2, -8, v218
	v_lshlrev_b64 v[2:3], 8, v[110:111]
	v_mad_i64_i32 v[0:1], s[8:9], v110, s18, v[102:103]
	v_lshl_add_u64 v[2:3], v[108:109], 0, v[2:3]
	global_load_dwordx4 v[52:55], v[0:1], off offset:16
	global_load_dwordx4 v[56:59], v[0:1], off
	global_load_dwordx4 v[4:7], v[0:1], off offset:32
	global_load_dwordx4 v[62:65], v[0:1], off offset:48
	global_load_dwordx4 v[8:11], v[0:1], off offset:112
	global_load_dwordx4 v[16:19], v[0:1], off offset:96
	global_load_dwordx4 v[32:35], v[0:1], off offset:80
	global_load_dwordx4 v[48:51], v[0:1], off offset:64
	global_load_dwordx4 v[12:15], v[0:1], off offset:176
	global_load_dwordx4 v[20:23], v[0:1], off offset:160
	global_load_dwordx4 v[66:69], v[2:3], off
	global_load_dwordx4 v[70:73], v[2:3], off offset:16
	global_load_dwordx4 v[44:47], v[0:1], off offset:144
	s_nop 0
	global_load_dwordx4 v[0:3], v[0:1], off offset:128
	v_ashrrev_i32_e32 v61, 31, v60
	v_lshlrev_b64 v[116:117], 13, v[60:61]
	v_and_or_b32 v116, v110, s17, v116
	v_lshlrev_b64 v[80:81], 6, v[110:111]
	v_lshl_add_u64 v[120:121], s[38:39], 0, v[80:81]
	v_lshl_add_u64 v[118:119], s[22:23], 0, v[80:81]
	s_add_i32 s40, s40, s28
	s_cmpk_lt_i32 s40, 0x100
	s_waitcnt vmcnt(17)
	v_and_b32_e32 v61, 0xffff0000, v25
	s_waitcnt vmcnt(16)
	v_lshlrev_b32_e32 v77, 16, v29
	v_lshlrev_b32_e32 v76, 16, v28
	v_and_b32_e32 v29, 0xffff0000, v29
	v_and_b32_e32 v28, 0xffff0000, v28
	s_waitcnt vmcnt(15)
	v_lshlrev_b32_e32 v82, 16, v36
	v_and_b32_e32 v83, 0xffff0000, v36
	v_lshlrev_b32_e32 v36, 16, v37
	v_and_b32_e32 v37, 0xffff0000, v37
	s_waitcnt vmcnt(14)
	v_lshlrev_b32_e32 v90, 16, v41
	v_and_b32_e32 v91, 0xffff0000, v41
	v_lshlrev_b32_e32 v41, 16, v43
	v_lshlrev_b32_e32 v85, 16, v40
	v_and_b32_e32 v87, 0xffff0000, v40
	v_pk_mov_b32 v[88:89], v[38:39], v[42:43] op_sel:[1,0]
	v_pk_mul_f32 v[28:29], v[28:29], v[28:29]
	v_mul_f32_e32 v93, v90, v90
	v_mul_f32_e32 v91, v91, v91
	v_mul_f32_e32 v40, v83, v83
	v_mul_f32_e32 v90, v37, v37
	v_lshlrev_b32_e32 v60, 16, v25
	v_lshlrev_b32_e32 v75, 16, v24
	v_and_b32_e32 v25, 0xffff0000, v24
	v_and_b32_e32 v24, 0xffff0000, v26
	v_and_b32_e32 v92, 0xffff0000, v43
	v_lshlrev_b32_e32 v84, 16, v38
	v_and_b32_e32 v86, 0xffff0000, v38
	v_lshlrev_b32_e32 v43, 16, v42
	v_lshlrev_b32_e32 v42, 16, v39
	v_mul_f32_e32 v38, v61, v61
	v_and_b32_e32 v39, 0xffff0000, v89
	v_pk_fma_f32 v[28:29], v[76:77], v[76:77], v[28:29]
	v_pk_fma_f32 v[76:77], v[82:83], v[82:83], v[40:41] op_sel_hi:[1,1,0]
	v_pk_fma_f32 v[36:37], v[36:37], v[36:37], v[90:91] op_sel_hi:[1,1,0]
	v_lshlrev_b32_e32 v74, 16, v26
	v_pk_mul_f32 v[24:25], v[24:25], v[24:25]
	v_pk_mul_f32 v[86:87], v[86:87], v[86:87]
	v_pk_fma_f32 v[60:61], v[60:61], v[60:61], v[38:39] op_sel_hi:[1,1,0]
	v_mov_b32_e32 v77, v93
	v_mov_b32_e32 v37, v91
	v_and_b32_e32 v38, 0xffff0000, v88
	v_pk_fma_f32 v[24:25], v[74:75], v[74:75], v[24:25]
	v_pk_fma_f32 v[74:75], v[84:85], v[84:85], v[86:87]
	v_pk_add_f32 v[36:37], v[76:77], v[36:37]
	v_pk_mul_f32 v[38:39], v[38:39], v[38:39]
	v_lshlrev_b32_e32 v26, 16, v27
	v_and_b32_e32 v27, 0xffff0000, v27
	v_pk_add_f32 v[36:37], v[74:75], v[36:37]
	v_pk_fma_f32 v[38:39], v[42:43], v[42:43], v[38:39]
	v_lshlrev_b32_e32 v79, 16, v31
	v_lshlrev_b32_e32 v78, 16, v30
	v_and_b32_e32 v31, 0xffff0000, v31
	v_and_b32_e32 v30, 0xffff0000, v30
	v_pk_add_f32 v[60:61], v[24:25], v[60:61] op_sel:[1,0] op_sel_hi:[0,1]
	v_pk_add_f32 v[36:37], v[38:39], v[36:37]
	v_mul_f32_e32 v38, v27, v27
	v_pk_mul_f32 v[30:31], v[30:31], v[30:31]
	v_pk_add_f32 v[24:25], v[24:25], v[60:61]
	v_pk_fma_f32 v[26:27], v[26:27], v[26:27], v[38:39] op_sel_hi:[1,1,0]
	v_pk_fma_f32 v[30:31], v[78:79], v[78:79], v[30:31]
	v_pk_add_f32 v[28:29], v[28:29], v[28:29] op_sel:[0,1] op_sel_hi:[1,0]
	v_mov_b32_e32 v40, v26
	v_mov_b32_e32 v38, v24
	v_mov_b32_e32 v39, v41
	v_pk_add_f32 v[28:29], v[30:31], v[28:29]
	v_pk_add_f32 v[24:25], v[26:27], v[24:25]
	v_pk_mul_f32 v[26:27], v[40:41], v[38:39]
	v_mul_f32_e32 v92, v92, v92
	v_mov_b32_e32 v25, v27
	v_pk_add_f32 v[26:27], v[30:31], v[28:29] op_sel:[1,0] op_sel_hi:[0,1]
	v_mov_b32_e32 v27, v92
	v_pk_add_f32 v[24:25], v[24:25], v[26:27]
	s_waitcnt vmcnt(2)
	v_and_b32_e32 v27, 0xffff0000, v70
	v_pk_add_f32 v[24:25], v[24:25], v[36:37]
	v_and_b32_e32 v26, 0xffff0000, v66
	v_add_f32_e32 v30, v24, v25
	v_lshlrev_b32_e32 v25, 16, v70
	v_lshlrev_b32_e32 v24, 16, v66
	v_pk_mul_f32 v[26:27], v[26:27], v[26:27]
	v_and_b32_e32 v29, 0xffff0000, v71
	v_and_b32_e32 v28, 0xffff0000, v67
	v_pk_fma_f32 v[24:25], v[24:25], v[24:25], v[26:27]
	v_lshlrev_b32_e32 v27, 16, v71
	v_lshlrev_b32_e32 v26, 16, v67
	v_pk_mul_f32 v[28:29], v[28:29], v[28:29]
	v_and_b32_e32 v161, 0xffff0000, v52
	v_pk_fma_f32 v[26:27], v[26:27], v[26:27], v[28:29]
	v_and_b32_e32 v29, 0xffff0000, v72
	v_and_b32_e32 v28, 0xffff0000, v68
	v_pk_add_f32 v[24:25], v[24:25], v[26:27]
	v_lshlrev_b32_e32 v27, 16, v72
	v_lshlrev_b32_e32 v26, 16, v68
	v_pk_mul_f32 v[28:29], v[28:29], v[28:29]
	v_lshlrev_b32_e32 v160, 16, v52
	v_pk_fma_f32 v[26:27], v[26:27], v[26:27], v[28:29]
	v_and_b32_e32 v29, 0xffff0000, v73
	v_and_b32_e32 v28, 0xffff0000, v69
	v_pk_add_f32 v[24:25], v[26:27], v[24:25]
	v_lshlrev_b32_e32 v27, 16, v73
	v_lshlrev_b32_e32 v26, 16, v69
	v_pk_mul_f32 v[28:29], v[28:29], v[28:29]
	v_and_b32_e32 v163, 0xffff0000, v53
	v_pk_fma_f32 v[26:27], v[26:27], v[26:27], v[28:29]
	v_lshlrev_b32_e32 v162, 16, v53
	v_pk_add_f32 v[24:25], v[26:27], v[24:25]
	v_and_b32_e32 v85, 0xffff0000, v63
	v_add_f32_e32 v28, v24, v25
	v_mul_f32_e32 v24, v161, v161
	v_pk_fma_f32 v[60:61], v[160:161], v[160:161], v[24:25] op_sel_hi:[1,1,0]
	v_mul_f32_e32 v24, v163, v163
	v_and_b32_e32 v84, 0xffff0000, v62
	ds_swizzle_b32 v29, v30 offset:swizzle(SWAP,1)
	v_pk_fma_f32 v[52:53], v[162:163], v[162:163], v[24:25] op_sel_hi:[1,1,0]
	v_lshlrev_b32_e32 v123, 16, v63
	v_lshlrev_b32_e32 v122, 16, v62
	v_pk_mul_f32 v[24:25], v[84:85], v[84:85]
	v_and_b32_e32 v87, 0xffff0000, v65
	v_and_b32_e32 v86, 0xffff0000, v64
	v_pk_fma_f32 v[24:25], v[122:123], v[122:123], v[24:25]
	v_lshlrev_b32_e32 v129, 16, v65
	v_lshlrev_b32_e32 v128, 16, v64
	v_pk_mul_f32 v[26:27], v[86:87], v[86:87]
	v_pk_add_f32 v[24:25], v[24:25], v[24:25] op_sel:[0,1] op_sel_hi:[1,0]
	v_pk_fma_f32 v[26:27], v[128:129], v[128:129], v[26:27]
	v_and_b32_e32 v167, 0xffff0000, v48
	v_pk_add_f32 v[24:25], v[26:27], v[24:25]
	v_lshlrev_b32_e32 v166, 16, v48
	v_pk_add_f32 v[184:185], v[26:27], v[24:25] op_sel:[1,0] op_sel_hi:[0,1]
	s_waitcnt lgkmcnt(0)
	v_add_f32_e32 v25, v30, v29
	ds_swizzle_b32 v26, v25 offset:swizzle(SWAP,2)
	v_mul_f32_e32 v24, v167, v167
	v_pk_fma_f32 v[72:73], v[166:167], v[166:167], v[24:25] op_sel_hi:[1,1,0]
	v_and_b32_e32 v191, 0xffff0000, v58
	v_and_b32_e32 v195, 0xffff0000, v56
	s_waitcnt lgkmcnt(0)
	v_add_f32_e32 v25, v25, v26
	ds_swizzle_b32 v26, v25 offset:swizzle(SWAP,4)
	v_lshlrev_b32_e32 v188, 16, v59
	v_and_b32_e32 v189, 0xffff0000, v59
	v_lshlrev_b32_e32 v190, 16, v58
	v_and_b32_e32 v193, 0xffff0000, v57
	v_lshlrev_b32_e32 v194, 16, v56
	v_mov_b32_e32 v58, v191
	v_mov_b32_e32 v59, v195
	v_lshlrev_b32_e32 v192, 16, v57
	v_mul_f32_e32 v48, v193, v193
	v_mov_b32_e32 v56, v190
	v_mov_b32_e32 v57, v194
	v_pk_mul_f32 v[58:59], v[58:59], v[58:59]
	v_lshlrev_b32_e32 v170, 16, v49
	ds_swizzle_b32 v27, v28 offset:swizzle(SWAP,1)
	v_and_b32_e32 v171, 0xffff0000, v49
	v_pk_fma_f32 v[48:49], v[192:193], v[192:193], v[48:49] op_sel_hi:[1,1,0]
	v_pk_fma_f32 v[56:57], v[56:57], v[56:57], v[58:59]
	v_and_b32_e32 v155, 0xffff0000, v4
	v_pk_add_f32 v[48:49], v[56:57], v[48:49] op_sel:[1,0] op_sel_hi:[0,1]
	v_and_b32_e32 v154, 0xffff0000, v54
	v_mul_f32_e32 v24, v171, v171
	v_pk_add_f32 v[56:57], v[56:57], v[48:49]
	v_lshlrev_b32_e32 v159, 16, v4
	v_lshlrev_b32_e32 v158, 16, v54
	v_pk_mul_f32 v[48:49], v[154:155], v[154:155]
	v_pk_fma_f32 v[76:77], v[170:171], v[170:171], v[24:25] op_sel_hi:[1,1,0]
	s_waitcnt lgkmcnt(1)
	v_add_f32_e32 v24, v25, v26
	v_pk_fma_f32 v[58:59], v[158:159], v[158:159], v[48:49]
	v_pk_mov_b32 v[48:49], v[54:55], v[6:7] op_sel:[1,0]
	v_fmamk_f32 v24, v24, 0x3b800000, v100
	v_and_b32_e32 v157, 0xffff0000, v49
	v_and_b32_e32 v156, 0xffff0000, v48
	s_waitcnt lgkmcnt(0)
	v_add_f32_e32 v25, v28, v27
	v_mul_f32_e32 v27, 0x4b800000, v24
	v_cmp_gt_f32_e32 vcc, s19, v24
	v_lshlrev_b32_e32 v173, 16, v6
	v_lshlrev_b32_e32 v172, 16, v55
	v_pk_mul_f32 v[48:49], v[156:157], v[156:157]
	s_waitcnt vmcnt(0)
	v_and_b32_e32 v145, 0xffff0000, v0
	v_and_b32_e32 v144, 0xffff0000, v50
	ds_swizzle_b32 v26, v25 offset:swizzle(SWAP,2)
	v_cndmask_b32_e32 v24, v24, v27, vcc
	v_pk_fma_f32 v[54:55], v[172:173], v[172:173], v[48:49]
	v_lshlrev_b32_e32 v143, 16, v0
	v_lshlrev_b32_e32 v142, 16, v50
	v_pk_mul_f32 v[48:49], v[144:145], v[144:145]
	v_rsq_f32_e32 v24, v24
	v_pk_fma_f32 v[202:203], v[142:143], v[142:143], v[48:49]
	v_pk_mov_b32 v[48:49], v[50:51], v[2:3] op_sel:[1,0]
	v_lshlrev_b32_e32 v139, 16, v2
	v_and_b32_e32 v141, 0xffff0000, v49
	v_and_b32_e32 v140, 0xffff0000, v48
	v_lshlrev_b32_e32 v138, 16, v51
	v_pk_mul_f32 v[48:49], v[140:141], v[140:141]
	v_and_b32_e32 v99, 0xffff0000, v44
	v_and_b32_e32 v98, 0xffff0000, v32
	v_and_b32_e32 v91, 0xffff0000, v45
	v_and_b32_e32 v90, 0xffff0000, v33
	v_pk_fma_f32 v[204:205], v[138:139], v[138:139], v[48:49]
	v_lshlrev_b32_e32 v97, 16, v44
	v_lshlrev_b32_e32 v96, 16, v32
	v_pk_mul_f32 v[48:49], v[98:99], v[98:99]
	v_lshlrev_b32_e32 v89, 16, v45
	v_lshlrev_b32_e32 v88, 16, v33
	v_pk_mul_f32 v[32:33], v[90:91], v[90:91]
	v_and_b32_e32 v127, 0xffff0000, v46
	v_and_b32_e32 v126, 0xffff0000, v34
	s_waitcnt lgkmcnt(0)
	v_add_f32_e32 v75, v25, v26
	v_mul_f32_e32 v25, 0x45800000, v24
	v_pk_fma_f32 v[48:49], v[96:97], v[96:97], v[48:49]
	v_pk_fma_f32 v[32:33], v[88:89], v[88:89], v[32:33]
	v_lshlrev_b32_e32 v125, 16, v46
	v_lshlrev_b32_e32 v124, 16, v34
	v_pk_mul_f32 v[44:45], v[126:127], v[126:127]
	v_and_b32_e32 v95, 0xffff0000, v47
	v_and_b32_e32 v94, 0xffff0000, v35
	v_cndmask_b32_e32 v219, v24, v25, vcc
	global_load_dwordx4 v[24:27], v101, s[44:45] offset:48
	global_load_dwordx4 v[28:31], v101, s[44:45] offset:32
	global_load_dwordx4 v[36:39], v101, s[44:45] offset:16
	global_load_dwordx4 v[40:43], v101, s[44:45]
	v_pk_add_f32 v[32:33], v[48:49], v[32:33]
	v_pk_fma_f32 v[44:45], v[124:125], v[124:125], v[44:45]
	v_lshlrev_b32_e32 v93, 16, v47
	v_lshlrev_b32_e32 v92, 16, v35
	v_pk_mul_f32 v[34:35], v[94:95], v[94:95]
	v_pk_add_f32 v[32:33], v[44:45], v[32:33]
	v_pk_fma_f32 v[34:35], v[92:93], v[92:93], v[34:35]
	v_and_b32_e32 v179, 0xffff0000, v20
	v_and_b32_e32 v178, 0xffff0000, v16
	v_and_b32_e32 v169, 0xffff0000, v21
	v_and_b32_e32 v168, 0xffff0000, v17
	v_pk_add_f32 v[32:33], v[34:35], v[32:33]
	v_lshlrev_b32_e32 v177, 16, v20
	v_lshlrev_b32_e32 v176, 16, v16
	v_pk_mul_f32 v[34:35], v[178:179], v[178:179]
	v_lshlrev_b32_e32 v165, 16, v21
	v_lshlrev_b32_e32 v164, 16, v17
	v_pk_mul_f32 v[16:17], v[168:169], v[168:169]
	v_and_b32_e32 v183, 0xffff0000, v22
	v_and_b32_e32 v182, 0xffff0000, v18
	v_pk_fma_f32 v[34:35], v[176:177], v[176:177], v[34:35]
	v_pk_fma_f32 v[16:17], v[164:165], v[164:165], v[16:17]
	v_lshlrev_b32_e32 v181, 16, v22
	v_lshlrev_b32_e32 v180, 16, v18
	v_pk_mul_f32 v[20:21], v[182:183], v[182:183]
	v_and_b32_e32 v175, 0xffff0000, v23
	v_and_b32_e32 v174, 0xffff0000, v19
	v_pk_add_f32 v[16:17], v[34:35], v[16:17]
	v_pk_fma_f32 v[20:21], v[180:181], v[180:181], v[20:21]
	v_lshlrev_b32_e32 v187, 16, v23
	v_lshlrev_b32_e32 v186, 16, v19
	v_pk_mul_f32 v[18:19], v[174:175], v[174:175]
	v_pk_add_f32 v[16:17], v[20:21], v[16:17]
	v_pk_fma_f32 v[18:19], v[186:187], v[186:187], v[18:19]
	v_and_b32_e32 v149, 0xffff0000, v12
	v_and_b32_e32 v148, 0xffff0000, v8
	v_and_b32_e32 v133, 0xffff0000, v13
	v_and_b32_e32 v132, 0xffff0000, v9
	v_pk_add_f32 v[34:35], v[18:19], v[16:17]
	v_lshlrev_b32_e32 v147, 16, v12
	v_lshlrev_b32_e32 v146, 16, v8
	v_pk_mul_f32 v[16:17], v[148:149], v[148:149]
	v_lshlrev_b32_e32 v131, 16, v13
	v_lshlrev_b32_e32 v130, 16, v9
	v_pk_mul_f32 v[8:9], v[132:133], v[132:133]
	v_pk_fma_f32 v[16:17], v[146:147], v[146:147], v[16:17]
	v_pk_fma_f32 v[8:9], v[130:131], v[130:131], v[8:9]
	v_and_b32_e32 v153, 0xffff0000, v14
	v_pk_add_f32 v[8:9], v[16:17], v[8:9]
	global_load_dwordx4 v[16:19], v101, s[44:45] offset:112
	global_load_dwordx4 v[20:23], v101, s[44:45] offset:96
	global_load_dwordx4 v[44:47], v101, s[44:45] offset:80
	global_load_dwordx4 v[48:51], v101, s[44:45] offset:64
	global_load_dwordx4 v[208:211], v101, s[44:45] offset:176
	global_load_dwordx4 v[212:215], v101, s[44:45] offset:160
	global_load_dwordx4 v[220:223], v101, s[44:45] offset:144
	global_load_dwordx4 v[224:227], v101, s[44:45] offset:128
	v_and_b32_e32 v152, 0xffff0000, v10
	v_lshlrev_b32_e32 v151, 16, v14
	v_lshlrev_b32_e32 v150, 16, v10
	v_pk_mul_f32 v[12:13], v[152:153], v[152:153]
	v_and_b32_e32 v137, 0xffff0000, v15
	v_and_b32_e32 v136, 0xffff0000, v11
	v_mul_f32_e32 v62, v189, v189
	v_pk_fma_f32 v[12:13], v[150:151], v[150:151], v[12:13]
	v_lshlrev_b32_e32 v135, 16, v15
	v_lshlrev_b32_e32 v134, 16, v11
	v_pk_mul_f32 v[10:11], v[136:137], v[136:137]
	v_lshlrev_b32_e32 v196, 16, v7
	v_and_b32_e32 v7, 0xffff0000, v7
	v_lshlrev_b32_e32 v198, 16, v5
	v_and_b32_e32 v199, 0xffff0000, v5
	v_mov_b32_e32 v63, v62
	v_pk_add_f32 v[8:9], v[12:13], v[8:9]
	v_pk_fma_f32 v[10:11], v[134:135], v[134:135], v[10:11]
	v_mov_b32_e32 v197, v7
	v_pk_mul_f32 v[4:5], v[198:199], v[198:199]
	v_pk_add_f32 v[216:217], v[10:11], v[8:9]
	v_and_b32_e32 v6, s0, v6
	v_pk_mov_b32 v[8:9], v[62:63], v[196:197] op_sel:[1,0]
	v_mov_b32_e32 v61, v4
	v_mov_b32_e32 v53, v5
	v_pk_mul_f32 v[6:7], v[6:7], v[6:7]
	v_pk_fma_f32 v[10:11], v[188:189], v[188:189], v[8:9]
	v_pk_mul_f32 v[8:9], v[196:197], v[8:9] op_sel_hi:[0,1]
	v_pk_add_f32 v[4:5], v[60:61], v[52:53]
	v_mov_b32_e32 v11, v9
	v_mov_b32_e32 v57, v7
	v_pk_add_f32 v[4:5], v[58:59], v[4:5]
	v_pk_add_f32 v[6:7], v[10:11], v[56:57]
	v_pk_add_f32 v[4:5], v[54:55], v[4:5]
	v_lshlrev_b32_e32 v200, 16, v3
	v_pk_add_f32 v[4:5], v[6:7], v[4:5]
	v_and_b32_e32 v201, 0xffff0000, v3
	v_pk_add_f32 v[206:207], v[4:5], v[4:5] op_sel:[0,1] op_sel_hi:[1,0]
	v_pk_mul_f32 v[2:3], v[200:201], v[200:201]
	ds_swizzle_b32 v79, v75 offset:swizzle(SWAP,4)
	v_mov_b32_e32 v185, v3
	v_mov_b32_e32 v207, v2
	v_pk_add_f32 v[2:3], v[206:207], v[184:185]
	v_lshlrev_b32_e32 v206, 16, v1
	v_and_b32_e32 v207, 0xffff0000, v1
	v_pk_mul_f32 v[0:1], v[206:207], v[206:207]
	v_mul_f32_e32 v74, v219, v219
	v_mov_b32_e32 v73, v0
	v_mov_b32_e32 v77, v1
	v_pk_add_f32 v[0:1], v[72:73], v[76:77]
	v_mov_b32_e32 v240, v88
	v_pk_add_f32 v[0:1], v[202:203], v[0:1]
	v_mov_b32_e32 v241, v90
	v_pk_add_f32 v[0:1], v[204:205], v[0:1]
	v_mad_u64_u32 v[82:83], s[8:9], v116, s35, v[112:113]
	v_pk_add_f32 v[0:1], v[2:3], v[0:1]
	v_mad_i32_i24 v83, v117, s35, v83
	v_pk_add_f32 v[0:1], v[0:1], v[32:33]
	v_mov_b32_e32 v228, v158
	v_pk_add_f32 v[0:1], v[0:1], v[34:35]
	v_mov_b32_e32 v229, v154
	v_pk_add_f32 v[0:1], v[0:1], v[216:217]
	global_load_dwordx4 v[12:15], v101, s[44:45] offset:240
	global_load_dwordx4 v[56:59], v101, s[44:45] offset:224
	global_load_dwordx4 v[64:67], v101, s[44:45] offset:208
	global_load_dwordx4 v[68:71], v101, s[44:45] offset:192
	global_load_dwordx4 v[4:7], v101, s[44:45] offset:304
	global_load_dwordx4 v[8:11], v101, s[44:45] offset:288
	global_load_dwordx4 v[60:63], v101, s[44:45] offset:256
	global_load_dwordx4 v[52:55], v101, s[44:45] offset:272
	v_pk_mul_f32 v[0:1], v[0:1], v[74:75] op_sel_hi:[1,0]
	v_mov_b32_e32 v230, v172
	v_mov_b32_e32 v74, v0
	v_mov_b32_e32 v78, v1
	s_waitcnt lgkmcnt(0)
	v_pk_add_f32 v[0:1], v[74:75], v[78:79]
	v_mov_b32_e32 v231, v156
	v_pk_fma_f32 v[184:185], v[0:1], s[14:15], v[100:101] op_sel_hi:[1,1,0]
	v_mov_b32_e32 v232, v142
	v_mul_f32_e32 v0, 0x4b800000, v184
	v_cmp_gt_f32_e32 vcc, s19, v184
	v_mov_b32_e32 v233, v144
	v_mov_b32_e32 v234, v138
	v_cndmask_b32_e32 v0, v184, v0, vcc
	v_rsq_f32_e32 v88, v0
	global_load_dwordx4 v[0:3], v101, s[44:45] offset:368
	global_load_dwordx4 v[32:35], v101, s[44:45] offset:352
	global_load_dwordx4 v[76:79], v101, s[44:45] offset:320
	global_load_dwordx4 v[72:75], v101, s[44:45] offset:336
	v_mov_b32_e32 v235, v140
	v_mov_b32_e32 v236, v96
	v_mul_f32_e32 v90, 0x45800000, v88
	v_cndmask_b32_e32 v88, v88, v90, vcc
	v_mul_f32_e32 v88, 0x3e16c740, v88
	v_mul_f32_e32 v88, v219, v88
	s_waitcnt vmcnt(21)
	v_pk_mul_f32 v[36:37], v[36:37], v[88:89] op_sel_hi:[1,0]
	s_waitcnt vmcnt(20)
	v_pk_mul_f32 v[40:41], v[40:41], v[88:89] op_sel_hi:[1,0]
	v_pk_mul_f32 v[190:191], v[36:37], v[190:191]
	v_pk_mul_f32 v[36:37], v[42:43], v[88:89] op_sel_hi:[1,0]
	v_pk_mul_f32 v[40:41], v[40:41], v[194:195]
	v_pk_mul_f32 v[42:43], v[36:37], v[192:193]
	v_pk_mul_f32 v[36:37], v[38:39], v[88:89] op_sel_hi:[1,0]
	v_cvt_pk_bf16_f32 v38, v190, v191
	v_pk_mul_f32 v[188:189], v[36:37], v[188:189]
	v_cvt_pk_bf16_f32 v36, v40, v41
	v_cvt_pk_bf16_f32 v37, v42, v43
	v_cvt_pk_bf16_f32 v39, v188, v189
	v_pk_mul_f32 v[24:25], v[24:25], v[88:89] op_sel_hi:[1,0]
	s_lshl_b32 s57, s33, 8
	v_mbcnt_lo_u32_b32 v244, -1, 0
	v_mbcnt_hi_u32_b32 v244, -1, v244
	v_mul_u32_u24_e32 v244, 0xd0, v244
	v_add_u32_e32 v244, s57, v244
	ds_write_b128 v244, v[36:39]
	v_pk_mul_f32 v[28:29], v[28:29], v[88:89] op_sel_hi:[1,0]
	v_mov_b32_e32 v237, v98
	v_pk_mul_f32 v[36:37], v[24:25], v[228:229]
	v_pk_mul_f32 v[24:25], v[30:31], v[88:89] op_sel_hi:[1,0]
	v_pk_mul_f32 v[28:29], v[28:29], v[160:161]
	v_pk_mul_f32 v[30:31], v[24:25], v[162:163]
	v_pk_mul_f32 v[24:25], v[26:27], v[88:89] op_sel_hi:[1,0]
	v_cvt_pk_bf16_f32 v26, v36, v37
	v_pk_mul_f32 v[38:39], v[24:25], v[230:231]
	v_cvt_pk_bf16_f32 v24, v28, v29
	v_cvt_pk_bf16_f32 v25, v30, v31
	v_cvt_pk_bf16_f32 v27, v38, v39
	ds_write_b128 v244, v[24:27] offset:16
	s_waitcnt vmcnt(12)
	v_pk_mul_f32 v[28:29], v[226:227], v[88:89] op_sel_hi:[1,0]
	v_pk_mul_f32 v[30:31], v[222:223], v[88:89] op_sel_hi:[1,0]
	v_pk_mul_f32 v[24:25], v[224:225], v[88:89] op_sel_hi:[1,0]
	v_pk_mul_f32 v[26:27], v[220:221], v[88:89] op_sel_hi:[1,0]
	v_pk_mul_f32 v[24:25], v[24:25], v[166:167]
	v_pk_mul_f32 v[26:27], v[26:27], v[232:233]
	v_pk_mul_f32 v[28:29], v[28:29], v[170:171]
	v_pk_mul_f32 v[30:31], v[30:31], v[234:235]
	v_cvt_pk_bf16_f32 v24, v24, v25
	v_cvt_pk_bf16_f32 v25, v28, v29
	v_cvt_pk_bf16_f32 v26, v26, v27
	v_cvt_pk_bf16_f32 v27, v30, v31
	v_mov_b32_e32 v238, v124
	v_mov_b32_e32 v239, v126
	v_mov_b32_e32 v242, v92
	v_mov_b32_e32 v243, v94
	ds_write_b128 v244, v[24:27] offset:64
	v_pk_mul_f32 v[28:29], v[88:89], v[214:215] op_sel_hi:[0,1]
	v_pk_mul_f32 v[30:31], v[88:89], v[210:211] op_sel_hi:[0,1]
	v_pk_mul_f32 v[24:25], v[88:89], v[212:213] op_sel_hi:[0,1]
	v_pk_mul_f32 v[26:27], v[88:89], v[208:209] op_sel_hi:[0,1]
	v_pk_mul_f32 v[24:25], v[24:25], v[236:237]
	v_pk_mul_f32 v[26:27], v[26:27], v[238:239]
	v_pk_mul_f32 v[28:29], v[28:29], v[240:241]
	v_pk_mul_f32 v[30:31], v[30:31], v[242:243]
	v_cvt_pk_bf16_f32 v24, v24, v25
	v_cvt_pk_bf16_f32 v25, v28, v29
	v_cvt_pk_bf16_f32 v26, v26, v27
	v_cvt_pk_bf16_f32 v27, v30, v31
	global_load_dwordx4 v[28:31], v[120:121], off
	global_load_dwordx4 v[36:39], v[118:119], off
	v_mov_b32_e32 v156, v173
	ds_write_b128 v244, v[24:27] offset:80
	global_load_dwordx4 v[24:27], v[118:119], off offset:16
	s_nop 0
	global_load_dwordx4 v[40:43], v[120:121], off offset:16
	v_mov_b32_e32 v154, v159
	v_pk_mul_f32 v[48:49], v[48:49], v[88:89] op_sel_hi:[1,0]
	v_pk_mul_f32 v[44:45], v[44:45], v[88:89] op_sel_hi:[1,0]
	v_pk_mul_f32 v[48:49], v[48:49], v[154:155]
	v_pk_mul_f32 v[154:155], v[44:45], v[156:157]
	v_pk_mul_f32 v[44:45], v[50:51], v[88:89] op_sel_hi:[1,0]
	v_mov_b32_e32 v160, v128
	v_pk_mul_f32 v[50:51], v[44:45], v[198:199]
	v_pk_mul_f32 v[44:45], v[46:47], v[88:89] op_sel_hi:[1,0]
	v_mov_b32_e32 v161, v86
	v_pk_mul_f32 v[156:157], v[44:45], v[196:197]
	v_cvt_pk_bf16_f32 v44, v48, v49
	v_cvt_pk_bf16_f32 v45, v50, v51
	v_cvt_pk_bf16_f32 v46, v154, v155
	v_cvt_pk_bf16_f32 v47, v156, v157
	v_pk_mul_f32 v[16:17], v[16:17], v[88:89] op_sel_hi:[1,0]
	v_mov_b32_e32 v159, v84
	v_mov_b32_e32 v84, v123
	ds_write_b128 v244, v[44:47] offset:32
	v_mov_b32_e32 v158, v122
	v_mov_b32_e32 v86, v129
	v_pk_mul_f32 v[44:45], v[16:17], v[160:161]
	v_pk_mul_f32 v[16:17], v[22:23], v[88:89] op_sel_hi:[1,0]
	v_pk_mul_f32 v[20:21], v[20:21], v[88:89] op_sel_hi:[1,0]
	v_pk_mul_f32 v[22:23], v[16:17], v[84:85]
	v_pk_mul_f32 v[16:17], v[18:19], v[88:89] op_sel_hi:[1,0]
	v_pk_mul_f32 v[20:21], v[20:21], v[158:159]
	v_pk_mul_f32 v[46:47], v[16:17], v[86:87]
	v_cvt_pk_bf16_f32 v16, v20, v21
	v_cvt_pk_bf16_f32 v17, v22, v23
	v_cvt_pk_bf16_f32 v18, v44, v45
	v_cvt_pk_bf16_f32 v19, v46, v47
	v_mov_b32_e32 v122, v176
	v_mov_b32_e32 v123, v178
	v_mov_b32_e32 v128, v180
	v_mov_b32_e32 v129, v182
	v_mov_b32_e32 v162, v164
	v_mov_b32_e32 v163, v168
	v_mov_b32_e32 v166, v186
	v_mov_b32_e32 v167, v174
	ds_write_b128 v244, v[16:19] offset:48
	s_waitcnt vmcnt(12)
	v_pk_mul_f32 v[20:21], v[88:89], v[70:71] op_sel_hi:[0,1]
	v_pk_mul_f32 v[22:23], v[88:89], v[66:67] op_sel_hi:[0,1]
	v_pk_mul_f32 v[16:17], v[88:89], v[68:69] op_sel_hi:[0,1]
	v_pk_mul_f32 v[18:19], v[88:89], v[64:65] op_sel_hi:[0,1]
	v_pk_mul_f32 v[16:17], v[16:17], v[122:123]
	v_pk_mul_f32 v[18:19], v[18:19], v[128:129]
	v_pk_mul_f32 v[20:21], v[20:21], v[162:163]
	v_pk_mul_f32 v[22:23], v[22:23], v[166:167]
	v_cvt_pk_bf16_f32 v16, v16, v17
	v_cvt_pk_bf16_f32 v17, v20, v21
	v_cvt_pk_bf16_f32 v18, v18, v19
	v_cvt_pk_bf16_f32 v19, v22, v23
	v_mov_b32_e32 v182, v181
	v_mov_b32_e32 v170, v146
	v_mov_b32_e32 v171, v148
	ds_write_b128 v244, v[16:19] offset:96
	v_mov_b32_e32 v144, v143
	v_mov_b32_e32 v140, v139
	v_pk_mul_f32 v[16:17], v[88:89], v[56:57] op_sel_hi:[0,1]
	v_pk_mul_f32 v[18:19], v[88:89], v[182:183] op_sel_hi:[0,1]
	v_mov_b32_e32 v172, v150
	v_mov_b32_e32 v173, v152
	v_mov_b32_e32 v174, v187
	v_pk_mul_f32 v[44:45], v[16:17], v[170:171]
	v_pk_mul_f32 v[12:13], v[88:89], v[12:13] op_sel_hi:[0,1]
	v_pk_mul_f32 v[16:17], v[88:89], v[144:145] op_sel_hi:[0,1]
	v_mov_b32_e32 v178, v177
	s_waitcnt vmcnt(4)
	v_pk_mul_f32 v[56:57], v[18:19], v[72:73]
	v_pk_mul_f32 v[18:19], v[88:89], v[140:141] op_sel_hi:[0,1]
	v_pk_mul_f32 v[20:21], v[88:89], v[206:207] op_sel_hi:[0,1]
	v_mov_b32_e32 v168, v165
	v_pk_mul_f32 v[22:23], v[88:89], v[200:201] op_sel_hi:[0,1]
	v_pk_mul_f32 v[46:47], v[12:13], v[172:173]
	v_pk_mul_f32 v[12:13], v[88:89], v[58:59] op_sel_hi:[0,1]
	v_pk_mul_f32 v[48:49], v[16:17], v[60:61]
	v_pk_mul_f32 v[16:17], v[88:89], v[178:179] op_sel_hi:[0,1]
	v_pk_mul_f32 v[52:53], v[18:19], v[52:53]
	v_pk_mul_f32 v[58:59], v[20:21], v[62:63]
	v_pk_mul_f32 v[20:21], v[88:89], v[168:169] op_sel_hi:[0,1]
	v_pk_mul_f32 v[54:55], v[22:23], v[54:55]
	v_pk_mul_f32 v[22:23], v[88:89], v[174:175] op_sel_hi:[0,1]
	v_pk_mul_f32 v[50:51], v[16:17], v[76:77]
	s_waitcnt vmcnt(3)
	v_pk_mul_f32 v[16:17], v[48:49], v[28:29]
	s_waitcnt vmcnt(0)
	v_pk_mul_f32 v[18:19], v[52:53], v[40:41]
	v_pk_mul_f32 v[60:61], v[20:21], v[78:79]
	v_pk_mul_f32 v[20:21], v[58:59], v[30:31]
	v_pk_mul_f32 v[62:63], v[22:23], v[74:75]
	v_pk_mul_f32 v[22:23], v[54:55], v[42:43]
	v_pk_fma_f32 v[16:17], v[50:51], v[36:37], v[16:17]
	v_pk_fma_f32 v[18:19], v[56:57], v[24:25], v[18:19]
	v_pk_fma_f32 v[20:21], v[60:61], v[38:39], v[20:21]
	v_pk_fma_f32 v[22:23], v[62:63], v[26:27], v[22:23]
	v_mov_b32_e32 v188, v130
	v_mov_b32_e32 v189, v132
	v_cvt_pk_bf16_f32 v16, v16, v17
	v_cvt_pk_bf16_f32 v17, v20, v21
	v_cvt_pk_bf16_f32 v18, v18, v19
	v_cvt_pk_bf16_f32 v19, v22, v23
	v_mov_b32_e32 v190, v134
	v_mov_b32_e32 v191, v136
	ds_write_b128 v244, v[16:19] offset:160
	v_pk_mul_f32 v[64:65], v[12:13], v[188:189]
	v_pk_mul_f32 v[12:13], v[88:89], v[14:15] op_sel_hi:[0,1]
	global_load_dwordx4 v[16:19], v[120:121], off offset:32
	global_load_dwordx4 v[20:23], v[118:119], off offset:32
	v_pk_mul_f32 v[66:67], v[12:13], v[190:191]
	v_cvt_pk_bf16_f32 v12, v44, v45
	v_cvt_pk_bf16_f32 v13, v64, v65
	v_cvt_pk_bf16_f32 v14, v46, v47
	v_cvt_pk_bf16_f32 v15, v66, v67
	ds_write_b128 v244, v[12:15] offset:112
	global_load_dwordx4 v[12:15], v[120:121], off offset:48
	s_nop 0
	global_load_dwordx4 v[44:47], v[118:119], off offset:48
	v_pk_mul_f32 v[28:29], v[50:51], v[28:29]
	v_mov_b32_e32 v98, v97
	v_pk_fma_f32 v[28:29], v[48:49], v[36:37], v[28:29] neg_lo:[0,0,1] neg_hi:[0,0,1]
	v_pk_mul_f32 v[36:37], v[56:57], v[40:41]
	v_mov_b32_e32 v148, v147
	v_pk_fma_f32 v[36:37], v[52:53], v[24:25], v[36:37] neg_lo:[0,0,1] neg_hi:[0,0,1]
	v_pk_mul_f32 v[24:25], v[60:61], v[30:31]
	v_mov_b32_e32 v152, v151
	v_pk_fma_f32 v[30:31], v[58:59], v[38:39], v[24:25] neg_lo:[0,0,1] neg_hi:[0,0,1]
	v_pk_mul_f32 v[24:25], v[62:63], v[42:43]
	v_mov_b32_e32 v126, v125
	v_pk_fma_f32 v[38:39], v[54:55], v[26:27], v[24:25] neg_lo:[0,0,1] neg_hi:[0,0,1]
	v_cvt_pk_bf16_f32 v24, v28, v29
	v_cvt_pk_bf16_f32 v25, v30, v31
	v_cvt_pk_bf16_f32 v26, v36, v37
	v_cvt_pk_bf16_f32 v27, v38, v39
	ds_write_b128 v244, v[24:27] offset:128
	v_mov_b32_e32 v90, v89
	v_mov_b32_e32 v132, v131
	v_pk_mul_f32 v[24:25], v[88:89], v[98:99] op_sel_hi:[0,1]
	v_pk_mul_f32 v[8:9], v[24:25], v[8:9]
	v_pk_mul_f32 v[24:25], v[88:89], v[148:149] op_sel_hi:[0,1]
	v_pk_mul_f32 v[24:25], v[24:25], v[32:33]
	v_mov_b32_e32 v94, v93
	v_mov_b32_e32 v136, v135
	v_lshlrev_b64 v[64:65], 11, v[110:111]
	v_lshl_add_u64 v[64:65], v[104:105], 0, v[64:65]
	v_cmp_gt_f32_e32 vcc, s19, v185
	v_lshl_add_u64 v[40:41], s[20:21], 0, v[80:81]
	v_mad_u64_u32 v[124:125], s[8:9], v116, s35, v[114:115]
	v_mad_i32_i24 v125, v117, s35, v125
	v_add_u32_e32 v110, s16, v110
	s_waitcnt vmcnt(3)
	v_pk_mul_f32 v[26:27], v[8:9], v[16:17]
	v_pk_mul_f32 v[16:17], v[24:25], v[16:17]
	s_waitcnt vmcnt(2)
	v_pk_fma_f32 v[26:27], v[24:25], v[20:21], v[26:27]
	v_pk_fma_f32 v[8:9], v[8:9], v[20:21], v[16:17] neg_lo:[0,0,1] neg_hi:[0,0,1]
	v_pk_mul_f32 v[16:17], v[88:89], v[152:153] op_sel_hi:[0,1]
	v_pk_mul_f32 v[0:1], v[16:17], v[0:1]
	v_pk_mul_f32 v[16:17], v[88:89], v[126:127] op_sel_hi:[0,1]
	v_pk_mul_f32 v[4:5], v[16:17], v[4:5]
	s_waitcnt vmcnt(1)
	v_pk_mul_f32 v[16:17], v[0:1], v[12:13]
	s_waitcnt vmcnt(0)
	v_pk_fma_f32 v[16:17], v[4:5], v[44:45], v[16:17] neg_lo:[0,0,1] neg_hi:[0,0,1]
	v_pk_mul_f32 v[4:5], v[4:5], v[12:13]
	s_nop 0
	v_pk_fma_f32 v[4:5], v[0:1], v[44:45], v[4:5]
	v_pk_mul_f32 v[0:1], v[88:89], v[90:91] op_sel_hi:[0,1]
	v_pk_mul_f32 v[0:1], v[0:1], v[10:11]
	v_pk_mul_f32 v[10:11], v[88:89], v[132:133] op_sel_hi:[0,1]
	v_pk_mul_f32 v[10:11], v[10:11], v[34:35]
	v_pk_mul_f32 v[12:13], v[0:1], v[18:19]
	s_nop 0
	v_pk_fma_f32 v[12:13], v[10:11], v[22:23], v[12:13]
	v_pk_mul_f32 v[10:11], v[10:11], v[18:19]
	s_nop 0
	v_pk_fma_f32 v[10:11], v[0:1], v[22:23], v[10:11] neg_lo:[0,0,1] neg_hi:[0,0,1]
	v_pk_mul_f32 v[0:1], v[88:89], v[94:95] op_sel_hi:[0,1]
	v_pk_mul_f32 v[0:1], v[0:1], v[6:7]
	v_pk_mul_f32 v[6:7], v[88:89], v[136:137] op_sel_hi:[0,1]
	v_pk_mul_f32 v[2:3], v[6:7], v[2:3]
	v_pk_mul_f32 v[6:7], v[0:1], v[14:15]
	s_nop 0
	v_pk_fma_f32 v[6:7], v[2:3], v[46:47], v[6:7]
	v_pk_mul_f32 v[2:3], v[2:3], v[14:15]
	s_nop 0
	v_pk_fma_f32 v[14:15], v[0:1], v[46:47], v[2:3] neg_lo:[0,0,1] neg_hi:[0,0,1]
	v_cvt_pk_bf16_f32 v0, v8, v9
	v_cvt_pk_bf16_f32 v1, v10, v11
	v_cvt_pk_bf16_f32 v2, v16, v17
	v_cvt_pk_bf16_f32 v3, v14, v15
	ds_write_b128 v244, v[0:3] offset:144
	s_nop 1
	v_cvt_pk_bf16_f32 v0, v26, v27
	v_cvt_pk_bf16_f32 v1, v12, v13
	v_cvt_pk_bf16_f32 v2, v4, v5
	v_cvt_pk_bf16_f32 v3, v6, v7
	ds_write_b128 v244, v[0:3] offset:176
	v_readfirstlane_b32 s58, v82
	v_readfirstlane_b32 s59, v83
	v_mbcnt_lo_u32_b32 v0, -1, 0
	v_mbcnt_hi_u32_b32 v0, -1, v0
	v_mov_b32_e32 v1, v0
	v_mul_u32_u24_e32 v2, 0xaaab, v1
	v_lshrrev_b32_e32 v2, 22, v2
	v_mul_u32_u24_e32 v3, 0x60, v2
	v_sub_u32_e32 v3, v1, v3
	v_mul_u32_u24_e32 v4, 0x1556, v3
	v_lshrrev_b32_e32 v4, 16, v4
	v_mul_u32_u24_e32 v5, 12, v4
	v_sub_u32_e32 v5, v3, v5
	v_lshl_add_u32 v6, v4, 3, v2
	v_mul_u32_u24_e32 v6, 0xd0, v6
	v_lshl_add_u32 v6, v5, 4, v6
	v_add_u32_e32 v6, s57, v6
	ds_read_b128 v[16:19], v6
	v_mul_u32_u24_e32 v10, 0x180000, v2
	v_lshl_add_u32 v10, v3, 4, v10
	v_add_u32_e32 v1, 0x40, v0
	v_mul_u32_u24_e32 v2, 0xaaab, v1
	v_lshrrev_b32_e32 v2, 22, v2
	v_mul_u32_u24_e32 v3, 0x60, v2
	v_sub_u32_e32 v3, v1, v3
	v_mul_u32_u24_e32 v4, 0x1556, v3
	v_lshrrev_b32_e32 v4, 16, v4
	v_mul_u32_u24_e32 v5, 12, v4
	v_sub_u32_e32 v5, v3, v5
	v_lshl_add_u32 v7, v4, 3, v2
	v_mul_u32_u24_e32 v7, 0xd0, v7
	v_lshl_add_u32 v7, v5, 4, v7
	v_add_u32_e32 v7, s57, v7
	ds_read_b128 v[20:23], v7
	v_mul_u32_u24_e32 v11, 0x180000, v2
	v_lshl_add_u32 v11, v3, 4, v11
	v_add_u32_e32 v1, 0x80, v0
	v_mul_u32_u24_e32 v2, 0xaaab, v1
	v_lshrrev_b32_e32 v2, 22, v2
	v_mul_u32_u24_e32 v3, 0x60, v2
	v_sub_u32_e32 v3, v1, v3
	v_mul_u32_u24_e32 v4, 0x1556, v3
	v_lshrrev_b32_e32 v4, 16, v4
	v_mul_u32_u24_e32 v5, 12, v4
	v_sub_u32_e32 v5, v3, v5
	v_lshl_add_u32 v8, v4, 3, v2
	v_mul_u32_u24_e32 v8, 0xd0, v8
	v_lshl_add_u32 v8, v5, 4, v8
	v_add_u32_e32 v8, s57, v8
	ds_read_b128 v[24:27], v8
	v_mul_u32_u24_e32 v12, 0x180000, v2
	v_lshl_add_u32 v12, v3, 4, v12
	v_add_u32_e32 v1, 0xc0, v0
	v_mul_u32_u24_e32 v2, 0xaaab, v1
	v_lshrrev_b32_e32 v2, 22, v2
	v_mul_u32_u24_e32 v3, 0x60, v2
	v_sub_u32_e32 v3, v1, v3
	v_mul_u32_u24_e32 v4, 0x1556, v3
	v_lshrrev_b32_e32 v4, 16, v4
	v_mul_u32_u24_e32 v5, 12, v4
	v_sub_u32_e32 v5, v3, v5
	v_lshl_add_u32 v9, v4, 3, v2
	v_mul_u32_u24_e32 v9, 0xd0, v9
	v_lshl_add_u32 v9, v5, 4, v9
	v_add_u32_e32 v9, s57, v9
	ds_read_b128 v[28:31], v9
	v_mul_u32_u24_e32 v13, 0x180000, v2
	v_lshl_add_u32 v13, v3, 4, v13
	s_waitcnt lgkmcnt(0)
	global_store_dwordx4 v10, v[16:19], s[58:59]
	global_store_dwordx4 v11, v[20:23], s[58:59]
	global_store_dwordx4 v12, v[24:27], s[58:59]
	global_store_dwordx4 v13, v[28:31], s[58:59]
	v_add_u32_e32 v1, 0x100, v0
	v_mul_u32_u24_e32 v2, 0xaaab, v1
	v_lshrrev_b32_e32 v2, 22, v2
	v_mul_u32_u24_e32 v3, 0x60, v2
	v_sub_u32_e32 v3, v1, v3
	v_mul_u32_u24_e32 v4, 0x1556, v3
	v_lshrrev_b32_e32 v4, 16, v4
	v_mul_u32_u24_e32 v5, 12, v4
	v_sub_u32_e32 v5, v3, v5
	v_lshl_add_u32 v6, v4, 3, v2
	v_mul_u32_u24_e32 v6, 0xd0, v6
	v_lshl_add_u32 v6, v5, 4, v6
	v_add_u32_e32 v6, s57, v6
	ds_read_b128 v[16:19], v6
	v_mul_u32_u24_e32 v10, 0x180000, v2
	v_lshl_add_u32 v10, v3, 4, v10
	v_add_u32_e32 v1, 0x140, v0
	v_mul_u32_u24_e32 v2, 0xaaab, v1
	v_lshrrev_b32_e32 v2, 22, v2
	v_mul_u32_u24_e32 v3, 0x60, v2
	v_sub_u32_e32 v3, v1, v3
	v_mul_u32_u24_e32 v4, 0x1556, v3
	v_lshrrev_b32_e32 v4, 16, v4
	v_mul_u32_u24_e32 v5, 12, v4
	v_sub_u32_e32 v5, v3, v5
	v_lshl_add_u32 v7, v4, 3, v2
	v_mul_u32_u24_e32 v7, 0xd0, v7
	v_lshl_add_u32 v7, v5, 4, v7
	v_add_u32_e32 v7, s57, v7
	ds_read_b128 v[20:23], v7
	v_mul_u32_u24_e32 v11, 0x180000, v2
	v_lshl_add_u32 v11, v3, 4, v11
	v_add_u32_e32 v1, 0x180, v0
	v_mul_u32_u24_e32 v2, 0xaaab, v1
	v_lshrrev_b32_e32 v2, 22, v2
	v_mul_u32_u24_e32 v3, 0x60, v2
	v_sub_u32_e32 v3, v1, v3
	v_mul_u32_u24_e32 v4, 0x1556, v3
	v_lshrrev_b32_e32 v4, 16, v4
	v_mul_u32_u24_e32 v5, 12, v4
	v_sub_u32_e32 v5, v3, v5
	v_lshl_add_u32 v8, v4, 3, v2
	v_mul_u32_u24_e32 v8, 0xd0, v8
	v_lshl_add_u32 v8, v5, 4, v8
	v_add_u32_e32 v8, s57, v8
	ds_read_b128 v[24:27], v8
	v_mul_u32_u24_e32 v12, 0x180000, v2
	v_lshl_add_u32 v12, v3, 4, v12
	v_add_u32_e32 v1, 0x1c0, v0
	v_mul_u32_u24_e32 v2, 0xaaab, v1
	v_lshrrev_b32_e32 v2, 22, v2
	v_mul_u32_u24_e32 v3, 0x60, v2
	v_sub_u32_e32 v3, v1, v3
	v_mul_u32_u24_e32 v4, 0x1556, v3
	v_lshrrev_b32_e32 v4, 16, v4
	v_mul_u32_u24_e32 v5, 12, v4
	v_sub_u32_e32 v5, v3, v5
	v_lshl_add_u32 v9, v4, 3, v2
	v_mul_u32_u24_e32 v9, 0xd0, v9
	v_lshl_add_u32 v9, v5, 4, v9
	v_add_u32_e32 v9, s57, v9
	ds_read_b128 v[28:31], v9
	v_mul_u32_u24_e32 v13, 0x180000, v2
	v_lshl_add_u32 v13, v3, 4, v13
	s_waitcnt lgkmcnt(0)
	global_store_dwordx4 v10, v[16:19], s[58:59]
	global_store_dwordx4 v11, v[20:23], s[58:59]
	global_store_dwordx4 v12, v[24:27], s[58:59]
	global_store_dwordx4 v13, v[28:31], s[58:59]
	v_add_u32_e32 v1, 0x200, v0
	v_mul_u32_u24_e32 v2, 0xaaab, v1
	v_lshrrev_b32_e32 v2, 22, v2
	v_mul_u32_u24_e32 v3, 0x60, v2
	v_sub_u32_e32 v3, v1, v3
	v_mul_u32_u24_e32 v4, 0x1556, v3
	v_lshrrev_b32_e32 v4, 16, v4
	v_mul_u32_u24_e32 v5, 12, v4
	v_sub_u32_e32 v5, v3, v5
	v_lshl_add_u32 v6, v4, 3, v2
	v_mul_u32_u24_e32 v6, 0xd0, v6
	v_lshl_add_u32 v6, v5, 4, v6
	v_add_u32_e32 v6, s57, v6
	ds_read_b128 v[16:19], v6
	v_mul_u32_u24_e32 v10, 0x180000, v2
	v_lshl_add_u32 v10, v3, 4, v10
	v_add_u32_e32 v1, 0x240, v0
	v_mul_u32_u24_e32 v2, 0xaaab, v1
	v_lshrrev_b32_e32 v2, 22, v2
	v_mul_u32_u24_e32 v3, 0x60, v2
	v_sub_u32_e32 v3, v1, v3
	v_mul_u32_u24_e32 v4, 0x1556, v3
	v_lshrrev_b32_e32 v4, 16, v4
	v_mul_u32_u24_e32 v5, 12, v4
	v_sub_u32_e32 v5, v3, v5
	v_lshl_add_u32 v7, v4, 3, v2
	v_mul_u32_u24_e32 v7, 0xd0, v7
	v_lshl_add_u32 v7, v5, 4, v7
	v_add_u32_e32 v7, s57, v7
	ds_read_b128 v[20:23], v7
	v_mul_u32_u24_e32 v11, 0x180000, v2
	v_lshl_add_u32 v11, v3, 4, v11
	v_add_u32_e32 v1, 0x280, v0
	v_mul_u32_u24_e32 v2, 0xaaab, v1
	v_lshrrev_b32_e32 v2, 22, v2
	v_mul_u32_u24_e32 v3, 0x60, v2
	v_sub_u32_e32 v3, v1, v3
	v_mul_u32_u24_e32 v4, 0x1556, v3
	v_lshrrev_b32_e32 v4, 16, v4
	v_mul_u32_u24_e32 v5, 12, v4
	v_sub_u32_e32 v5, v3, v5
	v_lshl_add_u32 v8, v4, 3, v2
	v_mul_u32_u24_e32 v8, 0xd0, v8
	v_lshl_add_u32 v8, v5, 4, v8
	v_add_u32_e32 v8, s57, v8
	ds_read_b128 v[24:27], v8
	v_mul_u32_u24_e32 v12, 0x180000, v2
	v_lshl_add_u32 v12, v3, 4, v12
	v_add_u32_e32 v1, 0x2c0, v0
	v_mul_u32_u24_e32 v2, 0xaaab, v1
	v_lshrrev_b32_e32 v2, 22, v2
	v_mul_u32_u24_e32 v3, 0x60, v2
	v_sub_u32_e32 v3, v1, v3
	v_mul_u32_u24_e32 v4, 0x1556, v3
	v_lshrrev_b32_e32 v4, 16, v4
	v_mul_u32_u24_e32 v5, 12, v4
	v_sub_u32_e32 v5, v3, v5
	v_lshl_add_u32 v9, v4, 3, v2
	v_mul_u32_u24_e32 v9, 0xd0, v9
	v_lshl_add_u32 v9, v5, 4, v9
	v_add_u32_e32 v9, s57, v9
	ds_read_b128 v[28:31], v9
	v_mul_u32_u24_e32 v13, 0x180000, v2
	v_lshl_add_u32 v13, v3, 4, v13
	s_waitcnt lgkmcnt(0)
	global_store_dwordx4 v10, v[16:19], s[58:59]
	global_store_dwordx4 v11, v[20:23], s[58:59]
	global_store_dwordx4 v12, v[24:27], s[58:59]
	global_store_dwordx4 v13, v[28:31], s[58:59]
	global_load_dwordx4 v[70:73], v[64:65], off offset:16
	global_load_dwordx4 v[32:35], v[64:65], off offset:48
	global_load_dwordx4 v[74:77], v[64:65], off offset:64
	global_load_dwordx4 v[84:87], v[64:65], off
	global_load_dwordx4 v[52:55], v[64:65], off offset:32
	v_mul_f32_e32 v0, 0x4b800000, v185
	global_load_dwordx4 v[88:91], v[64:65], off offset:80
	v_cndmask_b32_e32 v0, v185, v0, vcc
	v_rsq_f32_e32 v42, v0
	global_load_dwordx4 v[16:19], v[64:65], off offset:176
	global_load_dwordx4 v[20:23], v[64:65], off offset:160
	global_load_dwordx4 v[24:27], v[64:65], off offset:144
	global_load_dwordx4 v[28:31], v[64:65], off offset:128
	global_load_dwordx4 v[56:59], v[64:65], off offset:112
	global_load_dwordx4 v[150:153], v[64:65], off offset:96
	global_load_dwordx4 v[130:133], v[40:41], off offset:16
	global_load_dwordx4 v[36:39], v[40:41], off
	global_load_dwordx4 v[0:3], v[64:65], off offset:240
	global_load_dwordx4 v[4:7], v[64:65], off offset:224
	global_load_dwordx4 v[8:11], v[64:65], off offset:208
	global_load_dwordx4 v[12:15], v[64:65], off offset:192
	global_load_dwordx4 v[60:63], v[40:41], off offset:48
	global_load_dwordx4 v[154:157], v[40:41], off offset:32
	v_mul_f32_e32 v43, 0x45800000, v42
	v_cndmask_b32_e32 v122, v42, v43, vcc
	v_mul_f32_e32 v111, v122, v122
	s_waitcnt vmcnt(19)
	v_lshlrev_b32_e32 v202, 16, v70
	v_and_b32_e32 v203, 0xffff0000, v70
	v_lshlrev_b32_e32 v200, 16, v71
	s_waitcnt vmcnt(16)
	v_and_b32_e32 v69, 0xffff0000, v86
	v_and_b32_e32 v209, 0xffff0000, v84
	v_and_b32_e32 v201, 0xffff0000, v71
	v_lshlrev_b32_e32 v68, 16, v86
	v_lshlrev_b32_e32 v70, 16, v85
	v_and_b32_e32 v71, 0xffff0000, v85
	v_lshlrev_b32_e32 v208, 16, v84
	v_mov_b32_e32 v84, v69
	v_mov_b32_e32 v85, v209
	v_lshlrev_b32_e32 v192, 16, v74
	v_and_b32_e32 v193, 0xffff0000, v74
	v_mul_f32_e32 v74, v71, v71
	v_mov_b32_e32 v78, v68
	v_mov_b32_e32 v79, v208
	v_pk_mul_f32 v[84:85], v[84:85], v[84:85]
	v_lshlrev_b32_e32 v194, 16, v75
	v_and_b32_e32 v195, 0xffff0000, v75
	v_pk_fma_f32 v[74:75], v[70:71], v[70:71], v[74:75] op_sel_hi:[1,1,0]
	v_pk_fma_f32 v[78:79], v[78:79], v[78:79], v[84:85]
	s_waitcnt vmcnt(15)
	v_and_b32_e32 v175, 0xffff0000, v52
	v_pk_add_f32 v[74:75], v[78:79], v[74:75] op_sel:[1,0] op_sel_hi:[0,1]
	v_and_b32_e32 v174, 0xffff0000, v72
	v_pk_add_f32 v[84:85], v[78:79], v[74:75]
	v_lshlrev_b32_e32 v179, 16, v52
	v_lshlrev_b32_e32 v178, 16, v72
	v_pk_mul_f32 v[74:75], v[174:175], v[174:175]
	v_lshlrev_b32_e32 v206, 16, v87
	v_and_b32_e32 v207, 0xffff0000, v87
	v_pk_fma_f32 v[86:87], v[178:179], v[178:179], v[74:75]
	v_pk_mov_b32 v[74:75], v[72:73], v[54:55] op_sel:[1,0]
	v_lshlrev_b32_e32 v185, 16, v54
	v_and_b32_e32 v177, 0xffff0000, v75
	v_and_b32_e32 v176, 0xffff0000, v74
	v_lshlrev_b32_e32 v184, 16, v73
	v_pk_mul_f32 v[72:73], v[176:177], v[176:177]
	s_waitcnt vmcnt(6)
	v_and_b32_e32 v165, 0xffff0000, v36
	v_and_b32_e32 v164, 0xffff0000, v76
	v_pk_fma_f32 v[214:215], v[184:185], v[184:185], v[72:73]
	v_lshlrev_b32_e32 v163, 16, v36
	v_lshlrev_b32_e32 v162, 16, v76
	v_pk_mul_f32 v[72:73], v[164:165], v[164:165]
	v_lshlrev_b32_e32 v159, 16, v38
	v_pk_fma_f32 v[94:95], v[162:163], v[162:163], v[72:73]
	v_pk_mov_b32 v[72:73], v[76:77], v[38:39] op_sel:[1,0]
	v_lshlrev_b32_e32 v158, 16, v77
	v_and_b32_e32 v161, 0xffff0000, v73
	v_and_b32_e32 v160, 0xffff0000, v72
	v_pk_mul_f32 v[72:73], v[160:161], v[160:161]
	v_and_b32_e32 v137, 0xffff0000, v130
	v_and_b32_e32 v136, 0xffff0000, v88
	v_and_b32_e32 v129, 0xffff0000, v131
	v_and_b32_e32 v128, 0xffff0000, v89
	v_pk_fma_f32 v[96:97], v[158:159], v[158:159], v[72:73]
	v_lshlrev_b32_e32 v135, 16, v130
	v_lshlrev_b32_e32 v134, 16, v88
	v_pk_mul_f32 v[72:73], v[136:137], v[136:137]
	v_lshlrev_b32_e32 v127, 16, v131
	v_lshlrev_b32_e32 v126, 16, v89
	v_pk_mul_f32 v[74:75], v[128:129], v[128:129]
	v_pk_fma_f32 v[72:73], v[134:135], v[134:135], v[72:73]
	v_pk_fma_f32 v[74:75], v[126:127], v[126:127], v[74:75]
	v_and_b32_e32 v143, 0xffff0000, v132
	v_and_b32_e32 v142, 0xffff0000, v90
	v_pk_add_f32 v[72:73], v[72:73], v[74:75]
	v_lshlrev_b32_e32 v141, 16, v132
	v_lshlrev_b32_e32 v140, 16, v90
	v_pk_mul_f32 v[74:75], v[142:143], v[142:143]
	v_lshlrev_b32_e32 v131, 16, v133
	v_pk_fma_f32 v[74:75], v[140:141], v[140:141], v[74:75]
	v_and_b32_e32 v133, 0xffff0000, v133
	v_and_b32_e32 v132, 0xffff0000, v91
	v_and_b32_e32 v139, 0xffff0000, v33
	v_and_b32_e32 v138, 0xffff0000, v32
	v_pk_add_f32 v[72:73], v[74:75], v[72:73]
	v_lshlrev_b32_e32 v130, 16, v91
	v_pk_mul_f32 v[74:75], v[132:133], v[132:133]
	v_lshlrev_b32_e32 v147, 16, v33
	v_lshlrev_b32_e32 v146, 16, v32
	v_pk_mul_f32 v[32:33], v[138:139], v[138:139]
	v_and_b32_e32 v145, 0xffff0000, v35
	v_and_b32_e32 v144, 0xffff0000, v34
	v_pk_fma_f32 v[74:75], v[130:131], v[130:131], v[74:75]
	s_waitcnt vmcnt(0)
	v_and_b32_e32 v191, 0xffff0000, v154
	v_and_b32_e32 v190, 0xffff0000, v150
	v_and_b32_e32 v183, 0xffff0000, v155
	v_and_b32_e32 v182, 0xffff0000, v151
	v_pk_fma_f32 v[32:33], v[146:147], v[146:147], v[32:33]
	v_lshlrev_b32_e32 v149, 16, v35
	v_lshlrev_b32_e32 v148, 16, v34
	v_pk_mul_f32 v[34:35], v[144:145], v[144:145]
	v_pk_add_f32 v[236:237], v[74:75], v[72:73]
	v_lshlrev_b32_e32 v189, 16, v154
	v_lshlrev_b32_e32 v188, 16, v150
	v_pk_mul_f32 v[72:73], v[190:191], v[190:191]
	v_lshlrev_b32_e32 v181, 16, v155
	v_lshlrev_b32_e32 v180, 16, v151
	v_pk_mul_f32 v[74:75], v[182:183], v[182:183]
	v_pk_add_f32 v[32:33], v[32:33], v[32:33] op_sel:[0,1] op_sel_hi:[1,0]
	v_pk_fma_f32 v[34:35], v[148:149], v[148:149], v[34:35]
	v_pk_fma_f32 v[72:73], v[188:189], v[188:189], v[72:73]
	v_pk_fma_f32 v[74:75], v[180:181], v[180:181], v[74:75]
	v_and_b32_e32 v199, 0xffff0000, v156
	v_and_b32_e32 v198, 0xffff0000, v152
	v_pk_add_f32 v[32:33], v[34:35], v[32:33]
	v_pk_add_f32 v[72:73], v[72:73], v[74:75]
	v_lshlrev_b32_e32 v197, 16, v156
	v_lshlrev_b32_e32 v196, 16, v152
	v_pk_mul_f32 v[74:75], v[198:199], v[198:199]
	v_mul_f32_e32 v40, v203, v203
	v_pk_add_f32 v[92:93], v[34:35], v[32:33] op_sel:[1,0] op_sel_hi:[0,1]
	v_mul_f32_e32 v32, v193, v193
	v_pk_fma_f32 v[74:75], v[196:197], v[196:197], v[74:75]
	v_and_b32_e32 v187, 0xffff0000, v157
	v_and_b32_e32 v186, 0xffff0000, v153
	v_pk_fma_f32 v[80:81], v[202:203], v[202:203], v[40:41] op_sel_hi:[1,1,0]
	v_mul_f32_e32 v40, v201, v201
	v_pk_fma_f32 v[64:65], v[192:193], v[192:193], v[32:33] op_sel_hi:[1,1,0]
	v_mul_f32_e32 v32, v195, v195
	v_pk_add_f32 v[72:73], v[74:75], v[72:73]
	v_lshlrev_b32_e32 v205, 16, v157
	v_lshlrev_b32_e32 v204, 16, v153
	v_pk_mul_f32 v[74:75], v[186:187], v[186:187]
	v_pk_fma_f32 v[82:83], v[200:201], v[200:201], v[40:41] op_sel_hi:[1,1,0]
	v_pk_fma_f32 v[66:67], v[194:195], v[194:195], v[32:33] op_sel_hi:[1,1,0]
	global_load_dwordx4 v[32:35], v101, s[46:47] offset:48
	global_load_dwordx4 v[40:43], v101, s[46:47] offset:32
	global_load_dwordx4 v[44:47], v101, s[46:47] offset:16
	global_load_dwordx4 v[48:51], v101, s[46:47]
	v_pk_fma_f32 v[74:75], v[204:205], v[204:205], v[74:75]
	v_and_b32_e32 v169, 0xffff0000, v60
	v_and_b32_e32 v168, 0xffff0000, v56
	v_and_b32_e32 v153, 0xffff0000, v61
	v_and_b32_e32 v152, 0xffff0000, v57
	v_pk_add_f32 v[238:239], v[74:75], v[72:73]
	v_lshlrev_b32_e32 v167, 16, v60
	v_lshlrev_b32_e32 v166, 16, v56
	v_pk_mul_f32 v[72:73], v[168:169], v[168:169]
	v_lshlrev_b32_e32 v151, 16, v61
	v_lshlrev_b32_e32 v150, 16, v57
	v_pk_mul_f32 v[56:57], v[152:153], v[152:153]
	v_and_b32_e32 v173, 0xffff0000, v62
	v_and_b32_e32 v172, 0xffff0000, v58
	v_pk_fma_f32 v[72:73], v[166:167], v[166:167], v[72:73]
	v_pk_fma_f32 v[56:57], v[150:151], v[150:151], v[56:57]
	v_lshlrev_b32_e32 v171, 16, v62
	v_lshlrev_b32_e32 v170, 16, v58
	v_pk_mul_f32 v[60:61], v[172:173], v[172:173]
	v_and_b32_e32 v157, 0xffff0000, v63
	v_and_b32_e32 v156, 0xffff0000, v59
	v_pk_add_f32 v[56:57], v[72:73], v[56:57]
	v_pk_fma_f32 v[60:61], v[170:171], v[170:171], v[60:61]
	v_lshlrev_b32_e32 v155, 16, v63
	v_lshlrev_b32_e32 v154, 16, v59
	v_pk_mul_f32 v[58:59], v[156:157], v[156:157]
	v_pk_add_f32 v[56:57], v[60:61], v[56:57]
	v_pk_fma_f32 v[58:59], v[154:155], v[154:155], v[58:59]
	v_mul_f32_e32 v98, v207, v207
	v_pk_add_f32 v[240:241], v[58:59], v[56:57]
	global_load_dwordx4 v[56:59], v101, s[46:47] offset:112
	global_load_dwordx4 v[60:63], v101, s[46:47] offset:96
	global_load_dwordx4 v[72:75], v101, s[46:47] offset:80
	global_load_dwordx4 v[76:79], v101, s[46:47] offset:64
	global_load_dwordx4 v[220:223], v101, s[46:47] offset:144
	global_load_dwordx4 v[224:227], v101, s[46:47] offset:128
	global_load_dwordx4 v[228:231], v101, s[46:47] offset:176
	global_load_dwordx4 v[232:235], v101, s[46:47] offset:160
	v_lshlrev_b32_e32 v210, 16, v55
	v_and_b32_e32 v55, 0xffff0000, v55
	v_lshlrev_b32_e32 v212, 16, v53
	v_and_b32_e32 v213, 0xffff0000, v53
	v_mov_b32_e32 v99, v98
	v_mov_b32_e32 v211, v55
	v_pk_mul_f32 v[52:53], v[212:213], v[212:213]
	v_and_b32_e32 v54, s0, v54
	v_pk_mov_b32 v[88:89], v[98:99], v[210:211] op_sel:[1,0]
	v_mov_b32_e32 v81, v52
	v_mov_b32_e32 v83, v53
	v_pk_mul_f32 v[54:55], v[54:55], v[54:55]
	v_pk_fma_f32 v[90:91], v[206:207], v[206:207], v[88:89]
	v_pk_mul_f32 v[88:89], v[210:211], v[88:89] op_sel_hi:[0,1]
	v_pk_add_f32 v[52:53], v[80:81], v[82:83]
	v_mov_b32_e32 v91, v89
	v_mov_b32_e32 v85, v55
	v_pk_add_f32 v[52:53], v[86:87], v[52:53]
	v_lshlrev_b32_e32 v216, 16, v37
	v_and_b32_e32 v217, 0xffff0000, v37
	v_pk_add_f32 v[54:55], v[90:91], v[84:85]
	v_pk_add_f32 v[52:53], v[214:215], v[52:53]
	v_pk_mul_f32 v[36:37], v[216:217], v[216:217]
	v_pk_add_f32 v[52:53], v[54:55], v[52:53]
	v_lshlrev_b32_e32 v214, 16, v39
	v_and_b32_e32 v215, 0xffff0000, v39
	v_mov_b32_e32 v65, v36
	v_mov_b32_e32 v67, v37
	v_pk_add_f32 v[98:99], v[52:53], v[52:53] op_sel:[0,1] op_sel_hi:[1,0]
	v_pk_mul_f32 v[38:39], v[214:215], v[214:215]
	v_pk_add_f32 v[36:37], v[64:65], v[66:67]
	v_mov_b32_e32 v93, v39
	v_mov_b32_e32 v99, v38
	v_pk_add_f32 v[36:37], v[94:95], v[36:37]
	v_pk_add_f32 v[38:39], v[98:99], v[92:93]
	v_pk_add_f32 v[36:37], v[96:97], v[36:37]
	v_mov_b32_e32 v246, v162
	v_pk_add_f32 v[36:37], v[38:39], v[36:37]
	v_mov_b32_e32 v242, v178
	v_pk_add_f32 v[36:37], v[36:37], v[236:237]
	v_mov_b32_e32 v243, v174
	v_pk_add_f32 v[36:37], v[36:37], v[238:239]
	v_mov_b32_e32 v244, v184
	v_pk_add_f32 v[36:37], v[36:37], v[240:241]
	v_mov_b32_e32 v245, v176
	v_fmac_f32_e32 v37, v111, v36
	v_fmamk_f32 v36, v37, 0x3c2aaaab, v100
	v_mul_f32_e32 v37, 0x4b800000, v36
	v_cmp_gt_f32_e32 vcc, s19, v36
	global_load_dwordx4 v[52:55], v101, s[46:47] offset:240
	global_load_dwordx4 v[80:83], v101, s[46:47] offset:224
	global_load_dwordx4 v[84:87], v101, s[46:47] offset:208
	global_load_dwordx4 v[88:91], v101, s[46:47] offset:192
	v_cndmask_b32_e32 v36, v36, v37, vcc
	v_rsq_f32_e32 v111, v36
	global_load_dwordx4 v[36:39], v101, s[46:47] offset:304
	global_load_dwordx4 v[64:67], v101, s[46:47] offset:288
	global_load_dwordx4 v[96:99], v101, s[46:47] offset:256
	global_load_dwordx4 v[92:95], v101, s[46:47] offset:272
	v_mov_b32_e32 v247, v164
	v_mov_b32_e32 v240, v126
	v_mul_f32_e32 v123, 0x45800000, v111
	v_cndmask_b32_e32 v162, v111, v123, vcc
	v_mul_f32_e32 v178, v122, v162
	s_waitcnt vmcnt(18)
	v_pk_mul_f32 v[40:41], v[40:41], v[178:179] op_sel_hi:[1,0]
	v_pk_mul_f32 v[32:33], v[32:33], v[178:179] op_sel_hi:[1,0]
	v_pk_mul_f32 v[40:41], v[40:41], v[202:203]
	v_pk_mul_f32 v[202:203], v[32:33], v[242:243]
	v_pk_mul_f32 v[32:33], v[42:43], v[178:179] op_sel_hi:[1,0]
	s_waitcnt vmcnt(16)
	v_pk_mul_f32 v[48:49], v[48:49], v[178:179] op_sel_hi:[1,0]
	v_pk_mul_f32 v[200:201], v[32:33], v[200:201]
	v_pk_mul_f32 v[32:33], v[34:35], v[178:179] op_sel_hi:[1,0]
	v_pk_mul_f32 v[208:209], v[48:49], v[208:209]
	v_pk_mul_f32 v[44:45], v[44:45], v[178:179] op_sel_hi:[1,0]
	v_pk_mul_f32 v[48:49], v[50:51], v[178:179] op_sel_hi:[1,0]
	v_pk_mul_f32 v[46:47], v[46:47], v[178:179] op_sel_hi:[1,0]
	v_pk_mul_f32 v[244:245], v[32:33], v[244:245]
	v_pk_mul_f32 v[44:45], v[44:45], v[68:69]
	v_pk_mul_f32 v[236:237], v[48:49], v[70:71]
	v_pk_mul_f32 v[46:47], v[46:47], v[206:207]
	v_cvt_pk_bf16_f32 v32, v40, v41
	v_cvt_pk_bf16_f32 v33, v200, v201
	v_cvt_pk_bf16_f32 v34, v202, v203
	v_cvt_pk_bf16_f32 v35, v244, v245
	global_load_dwordx4 v[48:51], v101, s[46:47] offset:368
	global_load_dwordx4 v[68:71], v101, s[46:47] offset:352
	v_cvt_pk_bf16_f32 v206, v208, v209
	v_cvt_pk_bf16_f32 v207, v236, v237
	v_cvt_pk_bf16_f32 v208, v44, v45
	v_cvt_pk_bf16_f32 v209, v46, v47
	global_load_dwordx4 v[236:239], v101, s[46:47] offset:320
	global_load_dwordx4 v[44:47], v101, s[46:47] offset:336
	s_waitcnt vmcnt(14)
	v_pk_mul_f32 v[40:41], v[226:227], v[178:179] op_sel_hi:[1,0]
	s_lshl_b32 s57, s33, 8
	v_mbcnt_lo_u32_b32 v244, -1, 0
	v_mbcnt_hi_u32_b32 v244, -1, v244
	v_mul_u32_u24_e32 v244, 0xd0, v244
	v_add_u32_e32 v244, s57, v244
	ds_write_b128 v244, v[32:35] offset:16
	ds_write_b128 v244, v[206:209]
	v_pk_mul_f32 v[40:41], v[40:41], v[194:195]
	v_pk_mul_f32 v[32:33], v[224:225], v[178:179] op_sel_hi:[1,0]
	v_mov_b32_e32 v206, v158
	v_mov_b32_e32 v207, v160
	v_pk_mul_f32 v[32:33], v[32:33], v[192:193]
	v_pk_mul_f32 v[34:35], v[220:221], v[178:179] op_sel_hi:[1,0]
	v_pk_mul_f32 v[192:193], v[222:223], v[178:179] op_sel_hi:[1,0]
	v_pk_mul_f32 v[34:35], v[34:35], v[246:247]
	v_pk_mul_f32 v[192:193], v[192:193], v[206:207]
	v_cvt_pk_bf16_f32 v32, v32, v33
	v_cvt_pk_bf16_f32 v33, v40, v41
	v_cvt_pk_bf16_f32 v34, v34, v35
	v_cvt_pk_bf16_f32 v35, v192, v193
	v_mov_b32_e32 v42, v140
	v_mov_b32_e32 v43, v142
	ds_write_b128 v244, v[32:35] offset:64
	v_mov_b32_e32 v208, v134
	v_mov_b32_e32 v209, v136
	s_waitcnt vmcnt(13)
	v_pk_mul_f32 v[34:35], v[178:179], v[228:229] op_sel_hi:[0,1]
	v_mov_b32_e32 v241, v128
	v_mov_b32_e32 v242, v130
	v_mov_b32_e32 v243, v132
	s_waitcnt vmcnt(12)
	v_pk_mul_f32 v[32:33], v[178:179], v[232:233] op_sel_hi:[0,1]
	v_pk_mul_f32 v[34:35], v[34:35], v[42:43]
	v_pk_mul_f32 v[40:41], v[178:179], v[234:235] op_sel_hi:[0,1]
	v_pk_mul_f32 v[42:43], v[178:179], v[230:231] op_sel_hi:[0,1]
	v_pk_mul_f32 v[32:33], v[32:33], v[208:209]
	v_pk_mul_f32 v[40:41], v[40:41], v[240:241]
	v_pk_mul_f32 v[42:43], v[42:43], v[242:243]
	v_cvt_pk_bf16_f32 v32, v32, v33
	v_cvt_pk_bf16_f32 v33, v40, v41
	v_cvt_pk_bf16_f32 v34, v34, v35
	v_cvt_pk_bf16_f32 v35, v42, v43
	global_load_dwordx4 v[40:43], v[120:121], off
	global_load_dwordx4 v[192:195], v[118:119], off
	v_mov_b32_e32 v176, v185
	ds_write_b128 v244, v[32:35] offset:80
	global_load_dwordx4 v[32:35], v[118:119], off offset:16
	s_nop 0
	global_load_dwordx4 v[200:203], v[120:121], off offset:16
	v_mov_b32_e32 v174, v179
	v_pk_mul_f32 v[76:77], v[76:77], v[178:179] op_sel_hi:[1,0]
	v_pk_mul_f32 v[72:73], v[72:73], v[178:179] op_sel_hi:[1,0]
	v_pk_mul_f32 v[76:77], v[76:77], v[174:175]
	v_pk_mul_f32 v[174:175], v[72:73], v[176:177]
	v_pk_mul_f32 v[72:73], v[78:79], v[178:179] op_sel_hi:[1,0]
	v_mov_b32_e32 v206, v148
	v_pk_mul_f32 v[78:79], v[72:73], v[212:213]
	v_pk_mul_f32 v[72:73], v[74:75], v[178:179] op_sel_hi:[1,0]
	v_mov_b32_e32 v207, v144
	v_pk_mul_f32 v[176:177], v[72:73], v[210:211]
	v_cvt_pk_bf16_f32 v72, v76, v77
	v_cvt_pk_bf16_f32 v73, v78, v79
	v_cvt_pk_bf16_f32 v74, v174, v175
	v_cvt_pk_bf16_f32 v75, v176, v177
	v_pk_mul_f32 v[56:57], v[56:57], v[178:179] op_sel_hi:[1,0]
	v_mov_b32_e32 v185, v138
	v_mov_b32_e32 v138, v147
	ds_write_b128 v244, v[72:75] offset:32
	v_mov_b32_e32 v184, v146
	v_mov_b32_e32 v144, v149
	v_pk_mul_f32 v[72:73], v[56:57], v[206:207]
	v_pk_mul_f32 v[56:57], v[62:63], v[178:179] op_sel_hi:[1,0]
	v_pk_mul_f32 v[60:61], v[60:61], v[178:179] op_sel_hi:[1,0]
	v_pk_mul_f32 v[62:63], v[56:57], v[138:139]
	v_pk_mul_f32 v[56:57], v[58:59], v[178:179] op_sel_hi:[1,0]
	v_pk_mul_f32 v[60:61], v[60:61], v[184:185]
	v_pk_mul_f32 v[74:75], v[56:57], v[144:145]
	v_cvt_pk_bf16_f32 v56, v60, v61
	v_cvt_pk_bf16_f32 v57, v62, v63
	v_cvt_pk_bf16_f32 v58, v72, v73
	v_cvt_pk_bf16_f32 v59, v74, v75
	v_mov_b32_e32 v146, v188
	v_mov_b32_e32 v147, v190
	v_mov_b32_e32 v148, v196
	v_mov_b32_e32 v149, v198
	v_mov_b32_e32 v208, v180
	v_mov_b32_e32 v209, v182
	v_mov_b32_e32 v220, v204
	v_mov_b32_e32 v221, v186
	ds_write_b128 v244, v[56:59] offset:48
	s_waitcnt vmcnt(12)
	v_pk_mul_f32 v[60:61], v[178:179], v[90:91] op_sel_hi:[0,1]
	v_pk_mul_f32 v[62:63], v[178:179], v[86:87] op_sel_hi:[0,1]
	v_pk_mul_f32 v[56:57], v[178:179], v[88:89] op_sel_hi:[0,1]
	v_pk_mul_f32 v[58:59], v[178:179], v[84:85] op_sel_hi:[0,1]
	v_pk_mul_f32 v[56:57], v[56:57], v[146:147]
	v_pk_mul_f32 v[58:59], v[58:59], v[148:149]
	v_pk_mul_f32 v[60:61], v[60:61], v[208:209]
	v_pk_mul_f32 v[62:63], v[62:63], v[220:221]
	v_cvt_pk_bf16_f32 v56, v56, v57
	v_cvt_pk_bf16_f32 v57, v60, v61
	v_cvt_pk_bf16_f32 v58, v58, v59
	v_cvt_pk_bf16_f32 v59, v62, v63
	v_mov_b32_e32 v198, v197
	ds_write_b128 v244, v[56:59] offset:96
	v_mov_b32_e32 v160, v159
	v_mov_b32_e32 v182, v181
	v_pk_mul_f32 v[58:59], v[162:163], v[198:199] op_sel_hi:[0,1]
	s_waitcnt vmcnt(4)
	v_pk_mul_f32 v[76:77], v[58:59], v[44:45]
	v_pk_mul_f32 v[44:45], v[162:163], v[160:161] op_sel_hi:[0,1]
	v_pk_mul_f32 v[78:79], v[44:45], v[92:93]
	v_mov_b32_e32 v224, v170
	v_mov_b32_e32 v225, v172
	v_pk_mul_f32 v[56:57], v[178:179], v[80:81] op_sel_hi:[0,1]
	v_pk_mul_f32 v[52:53], v[178:179], v[52:53] op_sel_hi:[0,1]
	v_mov_b32_e32 v222, v166
	v_mov_b32_e32 v223, v168
	v_pk_mul_f32 v[62:63], v[52:53], v[224:225]
	v_pk_mul_f32 v[52:53], v[178:179], v[82:83] op_sel_hi:[0,1]
	v_mov_b32_e32 v164, v163
	v_mov_b32_e32 v186, v205
	v_pk_mul_f32 v[60:61], v[56:57], v[222:223]
	v_pk_mul_f32 v[56:57], v[162:163], v[164:165] op_sel_hi:[0,1]
	v_mov_b32_e32 v190, v189
	v_pk_mul_f32 v[72:73], v[56:57], v[96:97]
	v_pk_mul_f32 v[56:57], v[162:163], v[190:191] op_sel_hi:[0,1]
	v_pk_mul_f32 v[74:75], v[56:57], v[236:237]
	s_waitcnt vmcnt(3)
	v_pk_mul_f32 v[56:57], v[72:73], v[40:41]
	v_mov_b32_e32 v226, v150
	s_waitcnt vmcnt(0)
	v_pk_mul_f32 v[44:45], v[78:79], v[200:201]
	v_pk_fma_f32 v[56:57], v[74:75], v[192:193], v[56:57]
	v_pk_fma_f32 v[58:59], v[76:77], v[32:33], v[44:45]
	v_pk_mul_f32 v[44:45], v[162:163], v[216:217] op_sel_hi:[0,1]
	v_pk_mul_f32 v[80:81], v[44:45], v[98:99]
	v_pk_mul_f32 v[44:45], v[162:163], v[182:183] op_sel_hi:[0,1]
	v_pk_mul_f32 v[82:83], v[44:45], v[238:239]
	v_pk_mul_f32 v[44:45], v[80:81], v[42:43]
	v_mov_b32_e32 v227, v152
	v_pk_fma_f32 v[84:85], v[82:83], v[194:195], v[44:45]
	v_pk_mul_f32 v[44:45], v[162:163], v[214:215] op_sel_hi:[0,1]
	v_pk_mul_f32 v[86:87], v[44:45], v[94:95]
	v_pk_mul_f32 v[44:45], v[162:163], v[186:187] op_sel_hi:[0,1]
	v_pk_mul_f32 v[88:89], v[44:45], v[46:47]
	v_pk_mul_f32 v[44:45], v[86:87], v[202:203]
	v_cvt_pk_bf16_f32 v46, v58, v59
	v_pk_fma_f32 v[90:91], v[88:89], v[34:35], v[44:45]
	v_cvt_pk_bf16_f32 v44, v56, v57
	v_cvt_pk_bf16_f32 v45, v84, v85
	v_cvt_pk_bf16_f32 v47, v90, v91
	ds_write_b128 v244, v[44:47] offset:160
	v_mov_b32_e32 v228, v154
	v_mov_b32_e32 v229, v156
	global_load_dwordx4 v[44:47], v[120:121], off offset:32
	global_load_dwordx4 v[56:59], v[118:119], off offset:32
	v_pk_mul_f32 v[84:85], v[52:53], v[226:227]
	v_pk_mul_f32 v[52:53], v[178:179], v[54:55] op_sel_hi:[0,1]
	v_pk_mul_f32 v[90:91], v[52:53], v[228:229]
	v_cvt_pk_bf16_f32 v52, v60, v61
	v_cvt_pk_bf16_f32 v53, v84, v85
	v_cvt_pk_bf16_f32 v54, v62, v63
	v_cvt_pk_bf16_f32 v55, v90, v91
	ds_write_b128 v244, v[52:55] offset:112
	global_load_dwordx4 v[52:55], v[120:121], off offset:48
	s_nop 0
	global_load_dwordx4 v[60:63], v[118:119], off offset:48
	v_pk_mul_f32 v[40:41], v[74:75], v[40:41]
	v_mov_b32_e32 v136, v135
	v_pk_fma_f32 v[40:41], v[72:73], v[192:193], v[40:41] neg_lo:[0,0,1] neg_hi:[0,0,1]
	v_pk_mul_f32 v[72:73], v[76:77], v[200:201]
	v_mov_b32_e32 v168, v167
	v_pk_fma_f32 v[72:73], v[78:79], v[32:33], v[72:73] neg_lo:[0,0,1] neg_hi:[0,0,1]
	v_pk_mul_f32 v[32:33], v[82:83], v[42:43]
	v_mov_b32_e32 v172, v171
	v_pk_fma_f32 v[42:43], v[80:81], v[194:195], v[32:33] neg_lo:[0,0,1] neg_hi:[0,0,1]
	v_pk_mul_f32 v[32:33], v[88:89], v[202:203]
	v_mov_b32_e32 v142, v141
	v_pk_fma_f32 v[74:75], v[86:87], v[34:35], v[32:33] neg_lo:[0,0,1] neg_hi:[0,0,1]
	v_cvt_pk_bf16_f32 v32, v40, v41
	v_cvt_pk_bf16_f32 v33, v42, v43
	v_cvt_pk_bf16_f32 v34, v72, v73
	v_cvt_pk_bf16_f32 v35, v74, v75
	ds_write_b128 v244, v[32:35] offset:128
	v_pk_mul_f32 v[42:43], v[162:163], v[142:143] op_sel_hi:[0,1]
	v_pk_mul_f32 v[36:37], v[42:43], v[36:37]
	v_pk_mul_f32 v[32:33], v[162:163], v[136:137] op_sel_hi:[0,1]
	v_pk_mul_f32 v[32:33], v[32:33], v[64:65]
	v_pk_mul_f32 v[34:35], v[162:163], v[168:169] op_sel_hi:[0,1]
	v_pk_mul_f32 v[34:35], v[34:35], v[68:69]
	v_mov_b32_e32 v128, v127
	v_mov_b32_e32 v152, v151
	v_mov_b32_e32 v132, v131
	v_mov_b32_e32 v156, v155
	s_waitcnt vmcnt(3)
	v_pk_mul_f32 v[40:41], v[32:33], v[44:45]
	s_waitcnt vmcnt(2)
	v_pk_fma_f32 v[40:41], v[34:35], v[56:57], v[40:41]
	v_pk_mul_f32 v[34:35], v[34:35], v[44:45]
	v_pk_mul_f32 v[44:45], v[162:163], v[152:153] op_sel_hi:[0,1]
	v_pk_fma_f32 v[32:33], v[32:33], v[56:57], v[34:35] neg_lo:[0,0,1] neg_hi:[0,0,1]
	v_pk_mul_f32 v[34:35], v[162:163], v[172:173] op_sel_hi:[0,1]
	v_pk_mul_f32 v[34:35], v[34:35], v[48:49]
	v_pk_mul_f32 v[44:45], v[44:45], v[70:71]
	v_cvt_pk_bf16_f32 v32, v32, v33
	s_waitcnt vmcnt(1)
	v_pk_mul_f32 v[42:43], v[34:35], v[52:53]
	s_waitcnt vmcnt(0)
	v_pk_fma_f32 v[42:43], v[36:37], v[60:61], v[42:43] neg_lo:[0,0,1] neg_hi:[0,0,1]
	v_pk_mul_f32 v[36:37], v[36:37], v[52:53]
	s_nop 0
	v_pk_fma_f32 v[36:37], v[34:35], v[60:61], v[36:37]
	v_pk_mul_f32 v[34:35], v[162:163], v[128:129] op_sel_hi:[0,1]
	v_pk_mul_f32 v[34:35], v[34:35], v[66:67]
	s_nop 0
	v_pk_mul_f32 v[48:49], v[34:35], v[46:47]
	s_nop 0
	v_pk_fma_f32 v[48:49], v[44:45], v[58:59], v[48:49]
	v_pk_mul_f32 v[44:45], v[44:45], v[46:47]
	s_nop 0
	v_pk_fma_f32 v[34:35], v[34:35], v[58:59], v[44:45] neg_lo:[0,0,1] neg_hi:[0,0,1]
	v_pk_mul_f32 v[44:45], v[162:163], v[132:133] op_sel_hi:[0,1]
	v_pk_mul_f32 v[38:39], v[44:45], v[38:39]
	v_pk_mul_f32 v[44:45], v[162:163], v[156:157] op_sel_hi:[0,1]
	v_pk_mul_f32 v[44:45], v[44:45], v[50:51]
	v_pk_mul_f32 v[46:47], v[38:39], v[54:55]
	v_cvt_pk_bf16_f32 v33, v34, v35
	v_pk_fma_f32 v[46:47], v[44:45], v[62:63], v[46:47]
	v_pk_mul_f32 v[44:45], v[44:45], v[54:55]
	v_cvt_pk_bf16_f32 v34, v42, v43
	v_pk_fma_f32 v[38:39], v[38:39], v[62:63], v[44:45] neg_lo:[0,0,1] neg_hi:[0,0,1]
	s_nop 0
	v_cvt_pk_bf16_f32 v35, v38, v39
	ds_write_b128 v244, v[32:35] offset:144
	s_nop 1
	v_cvt_pk_bf16_f32 v32, v40, v41
	v_cvt_pk_bf16_f32 v33, v48, v49
	v_cvt_pk_bf16_f32 v34, v36, v37
	v_cvt_pk_bf16_f32 v35, v46, v47
	ds_write_b128 v244, v[32:35] offset:176
	v_readfirstlane_b32 s60, v124
	v_readfirstlane_b32 s61, v125
	v_mbcnt_lo_u32_b32 v42, -1, 0
	v_mbcnt_hi_u32_b32 v42, -1, v42
	v_mov_b32_e32 v43, v42
	v_mul_u32_u24_e32 v44, 0xaaab, v43
	v_lshrrev_b32_e32 v44, 22, v44
	v_mul_u32_u24_e32 v45, 0x60, v44
	v_sub_u32_e32 v45, v43, v45
	v_mul_u32_u24_e32 v46, 0x1556, v45
	v_lshrrev_b32_e32 v46, 16, v46
	v_mul_u32_u24_e32 v47, 12, v46
	v_sub_u32_e32 v47, v45, v47
	v_lshl_add_u32 v48, v46, 3, v44
	v_mul_u32_u24_e32 v48, 0xd0, v48
	v_lshl_add_u32 v48, v47, 4, v48
	v_add_u32_e32 v48, s57, v48
	ds_read_b128 v[60:63], v48
	v_mul_u32_u24_e32 v52, 0x180000, v44
	v_lshl_add_u32 v52, v45, 4, v52
	v_add_u32_e32 v43, 0x40, v42
	v_mul_u32_u24_e32 v44, 0xaaab, v43
	v_lshrrev_b32_e32 v44, 22, v44
	v_mul_u32_u24_e32 v45, 0x60, v44
	v_sub_u32_e32 v45, v43, v45
	v_mul_u32_u24_e32 v46, 0x1556, v45
	v_lshrrev_b32_e32 v46, 16, v46
	v_mul_u32_u24_e32 v47, 12, v46
	v_sub_u32_e32 v47, v45, v47
	v_lshl_add_u32 v49, v46, 3, v44
	v_mul_u32_u24_e32 v49, 0xd0, v49
	v_lshl_add_u32 v49, v47, 4, v49
	v_add_u32_e32 v49, s57, v49
	ds_read_b128 v[64:67], v49
	v_mul_u32_u24_e32 v53, 0x180000, v44
	v_lshl_add_u32 v53, v45, 4, v53
	v_add_u32_e32 v43, 0x80, v42
	v_mul_u32_u24_e32 v44, 0xaaab, v43
	v_lshrrev_b32_e32 v44, 22, v44
	v_mul_u32_u24_e32 v45, 0x60, v44
	v_sub_u32_e32 v45, v43, v45
	v_mul_u32_u24_e32 v46, 0x1556, v45
	v_lshrrev_b32_e32 v46, 16, v46
	v_mul_u32_u24_e32 v47, 12, v46
	v_sub_u32_e32 v47, v45, v47
	v_lshl_add_u32 v50, v46, 3, v44
	v_mul_u32_u24_e32 v50, 0xd0, v50
	v_lshl_add_u32 v50, v47, 4, v50
	v_add_u32_e32 v50, s57, v50
	ds_read_b128 v[68:71], v50
	v_mul_u32_u24_e32 v54, 0x180000, v44
	v_lshl_add_u32 v54, v45, 4, v54
	v_add_u32_e32 v43, 0xc0, v42
	v_mul_u32_u24_e32 v44, 0xaaab, v43
	v_lshrrev_b32_e32 v44, 22, v44
	v_mul_u32_u24_e32 v45, 0x60, v44
	v_sub_u32_e32 v45, v43, v45
	v_mul_u32_u24_e32 v46, 0x1556, v45
	v_lshrrev_b32_e32 v46, 16, v46
	v_mul_u32_u24_e32 v47, 12, v46
	v_sub_u32_e32 v47, v45, v47
	v_lshl_add_u32 v51, v46, 3, v44
	v_mul_u32_u24_e32 v51, 0xd0, v51
	v_lshl_add_u32 v51, v47, 4, v51
	v_add_u32_e32 v51, s57, v51
	ds_read_b128 v[72:75], v51
	v_mul_u32_u24_e32 v55, 0x180000, v44
	v_lshl_add_u32 v55, v45, 4, v55
	s_waitcnt lgkmcnt(0)
	global_store_dwordx4 v52, v[60:63], s[60:61]
	global_store_dwordx4 v53, v[64:67], s[60:61]
	global_store_dwordx4 v54, v[68:71], s[60:61]
	global_store_dwordx4 v55, v[72:75], s[60:61]
	v_add_u32_e32 v43, 0x100, v42
	v_mul_u32_u24_e32 v44, 0xaaab, v43
	v_lshrrev_b32_e32 v44, 22, v44
	v_mul_u32_u24_e32 v45, 0x60, v44
	v_sub_u32_e32 v45, v43, v45
	v_mul_u32_u24_e32 v46, 0x1556, v45
	v_lshrrev_b32_e32 v46, 16, v46
	v_mul_u32_u24_e32 v47, 12, v46
	v_sub_u32_e32 v47, v45, v47
	v_lshl_add_u32 v48, v46, 3, v44
	v_mul_u32_u24_e32 v48, 0xd0, v48
	v_lshl_add_u32 v48, v47, 4, v48
	v_add_u32_e32 v48, s57, v48
	ds_read_b128 v[60:63], v48
	v_mul_u32_u24_e32 v52, 0x180000, v44
	v_lshl_add_u32 v52, v45, 4, v52
	v_add_u32_e32 v43, 0x140, v42
	v_mul_u32_u24_e32 v44, 0xaaab, v43
	v_lshrrev_b32_e32 v44, 22, v44
	v_mul_u32_u24_e32 v45, 0x60, v44
	v_sub_u32_e32 v45, v43, v45
	v_mul_u32_u24_e32 v46, 0x1556, v45
	v_lshrrev_b32_e32 v46, 16, v46
	v_mul_u32_u24_e32 v47, 12, v46
	v_sub_u32_e32 v47, v45, v47
	v_lshl_add_u32 v49, v46, 3, v44
	v_mul_u32_u24_e32 v49, 0xd0, v49
	v_lshl_add_u32 v49, v47, 4, v49
	v_add_u32_e32 v49, s57, v49
	ds_read_b128 v[64:67], v49
	v_mul_u32_u24_e32 v53, 0x180000, v44
	v_lshl_add_u32 v53, v45, 4, v53
	v_add_u32_e32 v43, 0x180, v42
	v_mul_u32_u24_e32 v44, 0xaaab, v43
	v_lshrrev_b32_e32 v44, 22, v44
	v_mul_u32_u24_e32 v45, 0x60, v44
	v_sub_u32_e32 v45, v43, v45
	v_mul_u32_u24_e32 v46, 0x1556, v45
	v_lshrrev_b32_e32 v46, 16, v46
	v_mul_u32_u24_e32 v47, 12, v46
	v_sub_u32_e32 v47, v45, v47
	v_lshl_add_u32 v50, v46, 3, v44
	v_mul_u32_u24_e32 v50, 0xd0, v50
	v_lshl_add_u32 v50, v47, 4, v50
	v_add_u32_e32 v50, s57, v50
	ds_read_b128 v[68:71], v50
	v_mul_u32_u24_e32 v54, 0x180000, v44
	v_lshl_add_u32 v54, v45, 4, v54
	v_add_u32_e32 v43, 0x1c0, v42
	v_mul_u32_u24_e32 v44, 0xaaab, v43
	v_lshrrev_b32_e32 v44, 22, v44
	v_mul_u32_u24_e32 v45, 0x60, v44
	v_sub_u32_e32 v45, v43, v45
	v_mul_u32_u24_e32 v46, 0x1556, v45
	v_lshrrev_b32_e32 v46, 16, v46
	v_mul_u32_u24_e32 v47, 12, v46
	v_sub_u32_e32 v47, v45, v47
	v_lshl_add_u32 v51, v46, 3, v44
	v_mul_u32_u24_e32 v51, 0xd0, v51
	v_lshl_add_u32 v51, v47, 4, v51
	v_add_u32_e32 v51, s57, v51
	ds_read_b128 v[72:75], v51
	v_mul_u32_u24_e32 v55, 0x180000, v44
	v_lshl_add_u32 v55, v45, 4, v55
	s_waitcnt lgkmcnt(0)
	global_store_dwordx4 v52, v[60:63], s[60:61]
	global_store_dwordx4 v53, v[64:67], s[60:61]
	global_store_dwordx4 v54, v[68:71], s[60:61]
	global_store_dwordx4 v55, v[72:75], s[60:61]
	v_add_u32_e32 v43, 0x200, v42
	v_mul_u32_u24_e32 v44, 0xaaab, v43
	v_lshrrev_b32_e32 v44, 22, v44
	v_mul_u32_u24_e32 v45, 0x60, v44
	v_sub_u32_e32 v45, v43, v45
	v_mul_u32_u24_e32 v46, 0x1556, v45
	v_lshrrev_b32_e32 v46, 16, v46
	v_mul_u32_u24_e32 v47, 12, v46
	v_sub_u32_e32 v47, v45, v47
	v_lshl_add_u32 v48, v46, 3, v44
	v_mul_u32_u24_e32 v48, 0xd0, v48
	v_lshl_add_u32 v48, v47, 4, v48
	v_add_u32_e32 v48, s57, v48
	ds_read_b128 v[60:63], v48
	v_mul_u32_u24_e32 v52, 0x180000, v44
	v_lshl_add_u32 v52, v45, 4, v52
	v_add_u32_e32 v43, 0x240, v42
	v_mul_u32_u24_e32 v44, 0xaaab, v43
	v_lshrrev_b32_e32 v44, 22, v44
	v_mul_u32_u24_e32 v45, 0x60, v44
	v_sub_u32_e32 v45, v43, v45
	v_mul_u32_u24_e32 v46, 0x1556, v45
	v_lshrrev_b32_e32 v46, 16, v46
	v_mul_u32_u24_e32 v47, 12, v46
	v_sub_u32_e32 v47, v45, v47
	v_lshl_add_u32 v49, v46, 3, v44
	v_mul_u32_u24_e32 v49, 0xd0, v49
	v_lshl_add_u32 v49, v47, 4, v49
	v_add_u32_e32 v49, s57, v49
	ds_read_b128 v[64:67], v49
	v_mul_u32_u24_e32 v53, 0x180000, v44
	v_lshl_add_u32 v53, v45, 4, v53
	v_add_u32_e32 v43, 0x280, v42
	v_mul_u32_u24_e32 v44, 0xaaab, v43
	v_lshrrev_b32_e32 v44, 22, v44
	v_mul_u32_u24_e32 v45, 0x60, v44
	v_sub_u32_e32 v45, v43, v45
	v_mul_u32_u24_e32 v46, 0x1556, v45
	v_lshrrev_b32_e32 v46, 16, v46
	v_mul_u32_u24_e32 v47, 12, v46
	v_sub_u32_e32 v47, v45, v47
	v_lshl_add_u32 v50, v46, 3, v44
	v_mul_u32_u24_e32 v50, 0xd0, v50
	v_lshl_add_u32 v50, v47, 4, v50
	v_add_u32_e32 v50, s57, v50
	ds_read_b128 v[68:71], v50
	v_mul_u32_u24_e32 v54, 0x180000, v44
	v_lshl_add_u32 v54, v45, 4, v54
	v_add_u32_e32 v43, 0x2c0, v42
	v_mul_u32_u24_e32 v44, 0xaaab, v43
	v_lshrrev_b32_e32 v44, 22, v44
	v_mul_u32_u24_e32 v45, 0x60, v44
	v_sub_u32_e32 v45, v43, v45
	v_mul_u32_u24_e32 v46, 0x1556, v45
	v_lshrrev_b32_e32 v46, 16, v46
	v_mul_u32_u24_e32 v47, 12, v46
	v_sub_u32_e32 v47, v45, v47
	v_lshl_add_u32 v51, v46, 3, v44
	v_mul_u32_u24_e32 v51, 0xd0, v51
	v_lshl_add_u32 v51, v47, 4, v51
	v_add_u32_e32 v51, s57, v51
	ds_read_b128 v[72:75], v51
	v_mul_u32_u24_e32 v55, 0x180000, v44
	v_lshl_add_u32 v55, v45, 4, v55
	s_waitcnt lgkmcnt(0)
	global_store_dwordx4 v52, v[60:63], s[60:61]
	global_store_dwordx4 v53, v[64:67], s[60:61]
	global_store_dwordx4 v54, v[68:71], s[60:61]
	global_store_dwordx4 v55, v[72:75], s[60:61]
	s_nop 1
	v_lshlrev_b32_e32 v34, 16, v28
	v_and_b32_e32 v35, 0xffff0000, v28
	v_lshlrev_b32_e32 v28, 16, v29
	v_and_b32_e32 v29, 0xffff0000, v29
	v_pk_mul_f32 v[36:37], v[122:123], v[28:29] op_sel_hi:[0,1]
	v_lshlrev_b32_e32 v28, 16, v30
	v_and_b32_e32 v29, 0xffff0000, v30
	v_pk_mul_f32 v[38:39], v[122:123], v[28:29] op_sel_hi:[0,1]
	v_lshlrev_b32_e32 v28, 16, v31
	v_and_b32_e32 v29, 0xffff0000, v31
	v_lshlrev_b64 v[32:33], 7, v[116:117]
	v_pk_mul_f32 v[34:35], v[122:123], v[34:35] op_sel_hi:[0,1]
	v_pk_mul_f32 v[40:41], v[122:123], v[28:29] op_sel_hi:[0,1]
	v_lshl_add_u64 v[32:33], s[12:13], 0, v[32:33]
	v_cvt_pk_bf16_f32 v28, v34, v35
	v_cvt_pk_bf16_f32 v29, v36, v37
	v_cvt_pk_bf16_f32 v30, v38, v39
	v_cvt_pk_bf16_f32 v31, v40, v41
	s_lshl_b32 s57, s33, 8
	v_mbcnt_lo_u32_b32 v38, -1, 0
	v_mbcnt_hi_u32_b32 v38, -1, v38
	v_mul_u32_u24_e32 v38, 0x90, v38
	v_add_u32_e32 v38, s57, v38
	ds_write_b128 v38, v[28:31]
	s_nop 1
	v_lshlrev_b32_e32 v28, 16, v24
	v_and_b32_e32 v29, 0xffff0000, v24
	v_lshlrev_b32_e32 v24, 16, v25
	v_and_b32_e32 v25, 0xffff0000, v25
	v_pk_mul_f32 v[30:31], v[122:123], v[24:25] op_sel_hi:[0,1]
	v_lshlrev_b32_e32 v24, 16, v26
	v_and_b32_e32 v25, 0xffff0000, v26
	v_pk_mul_f32 v[34:35], v[122:123], v[24:25] op_sel_hi:[0,1]
	v_lshlrev_b32_e32 v24, 16, v27
	v_and_b32_e32 v25, 0xffff0000, v27
	v_pk_mul_f32 v[28:29], v[122:123], v[28:29] op_sel_hi:[0,1]
	v_pk_mul_f32 v[36:37], v[122:123], v[24:25] op_sel_hi:[0,1]
	v_cvt_pk_bf16_f32 v24, v28, v29
	v_cvt_pk_bf16_f32 v25, v30, v31
	v_cvt_pk_bf16_f32 v26, v34, v35
	v_cvt_pk_bf16_f32 v27, v36, v37
	ds_write_b128 v38, v[24:27] offset:16
	s_nop 1
	v_lshlrev_b32_e32 v24, 16, v20
	v_and_b32_e32 v25, 0xffff0000, v20
	v_lshlrev_b32_e32 v20, 16, v21
	v_and_b32_e32 v21, 0xffff0000, v21
	v_pk_mul_f32 v[26:27], v[122:123], v[20:21] op_sel_hi:[0,1]
	v_lshlrev_b32_e32 v20, 16, v22
	v_and_b32_e32 v21, 0xffff0000, v22
	v_pk_mul_f32 v[28:29], v[122:123], v[20:21] op_sel_hi:[0,1]
	v_lshlrev_b32_e32 v20, 16, v23
	v_and_b32_e32 v21, 0xffff0000, v23
	v_pk_mul_f32 v[24:25], v[122:123], v[24:25] op_sel_hi:[0,1]
	v_pk_mul_f32 v[30:31], v[122:123], v[20:21] op_sel_hi:[0,1]
	v_cvt_pk_bf16_f32 v20, v24, v25
	v_cvt_pk_bf16_f32 v21, v26, v27
	v_cvt_pk_bf16_f32 v22, v28, v29
	v_cvt_pk_bf16_f32 v23, v30, v31
	ds_write_b128 v38, v[20:23] offset:32
	s_nop 1
	v_lshlrev_b32_e32 v20, 16, v16
	v_and_b32_e32 v21, 0xffff0000, v16
	v_lshlrev_b32_e32 v16, 16, v17
	v_and_b32_e32 v17, 0xffff0000, v17
	v_pk_mul_f32 v[22:23], v[122:123], v[16:17] op_sel_hi:[0,1]
	v_lshlrev_b32_e32 v16, 16, v18
	v_and_b32_e32 v17, 0xffff0000, v18
	v_pk_mul_f32 v[24:25], v[122:123], v[16:17] op_sel_hi:[0,1]
	v_lshlrev_b32_e32 v16, 16, v19
	v_and_b32_e32 v17, 0xffff0000, v19
	v_pk_mul_f32 v[20:21], v[122:123], v[20:21] op_sel_hi:[0,1]
	v_pk_mul_f32 v[26:27], v[122:123], v[16:17] op_sel_hi:[0,1]
	v_cvt_pk_bf16_f32 v16, v20, v21
	v_cvt_pk_bf16_f32 v17, v22, v23
	v_cvt_pk_bf16_f32 v18, v24, v25
	v_cvt_pk_bf16_f32 v19, v26, v27
	ds_write_b128 v38, v[16:19] offset:48
	s_nop 1
	v_lshlrev_b32_e32 v16, 16, v12
	v_and_b32_e32 v17, 0xffff0000, v12
	v_lshlrev_b32_e32 v12, 16, v13
	v_and_b32_e32 v13, 0xffff0000, v13
	v_pk_mul_f32 v[18:19], v[122:123], v[12:13] op_sel_hi:[0,1]
	v_lshlrev_b32_e32 v12, 16, v14
	v_and_b32_e32 v13, 0xffff0000, v14
	v_pk_mul_f32 v[20:21], v[122:123], v[12:13] op_sel_hi:[0,1]
	v_lshlrev_b32_e32 v12, 16, v15
	v_and_b32_e32 v13, 0xffff0000, v15
	v_pk_mul_f32 v[16:17], v[122:123], v[16:17] op_sel_hi:[0,1]
	v_pk_mul_f32 v[22:23], v[122:123], v[12:13] op_sel_hi:[0,1]
	v_cvt_pk_bf16_f32 v12, v16, v17
	v_cvt_pk_bf16_f32 v13, v18, v19
	v_cvt_pk_bf16_f32 v14, v20, v21
	v_cvt_pk_bf16_f32 v15, v22, v23
	ds_write_b128 v38, v[12:15] offset:64
	s_nop 1
	v_lshlrev_b32_e32 v12, 16, v8
	v_and_b32_e32 v13, 0xffff0000, v8
	v_lshlrev_b32_e32 v8, 16, v9
	v_and_b32_e32 v9, 0xffff0000, v9
	v_pk_mul_f32 v[14:15], v[122:123], v[8:9] op_sel_hi:[0,1]
	v_lshlrev_b32_e32 v8, 16, v10
	v_and_b32_e32 v9, 0xffff0000, v10
	v_pk_mul_f32 v[16:17], v[122:123], v[8:9] op_sel_hi:[0,1]
	v_lshlrev_b32_e32 v8, 16, v11
	v_and_b32_e32 v9, 0xffff0000, v11
	v_pk_mul_f32 v[12:13], v[122:123], v[12:13] op_sel_hi:[0,1]
	v_pk_mul_f32 v[18:19], v[122:123], v[8:9] op_sel_hi:[0,1]
	v_cvt_pk_bf16_f32 v8, v12, v13
	v_cvt_pk_bf16_f32 v9, v14, v15
	v_cvt_pk_bf16_f32 v10, v16, v17
	v_cvt_pk_bf16_f32 v11, v18, v19
	ds_write_b128 v38, v[8:11] offset:80
	s_nop 1
	v_lshlrev_b32_e32 v8, 16, v4
	v_and_b32_e32 v9, 0xffff0000, v4
	v_lshlrev_b32_e32 v4, 16, v5
	v_and_b32_e32 v5, 0xffff0000, v5
	v_pk_mul_f32 v[10:11], v[122:123], v[4:5] op_sel_hi:[0,1]
	v_lshlrev_b32_e32 v4, 16, v6
	v_and_b32_e32 v5, 0xffff0000, v6
	v_pk_mul_f32 v[12:13], v[122:123], v[4:5] op_sel_hi:[0,1]
	v_lshlrev_b32_e32 v4, 16, v7
	v_and_b32_e32 v5, 0xffff0000, v7
	v_pk_mul_f32 v[8:9], v[122:123], v[8:9] op_sel_hi:[0,1]
	v_pk_mul_f32 v[14:15], v[122:123], v[4:5] op_sel_hi:[0,1]
	v_cvt_pk_bf16_f32 v4, v8, v9
	v_cvt_pk_bf16_f32 v5, v10, v11
	v_cvt_pk_bf16_f32 v6, v12, v13
	v_cvt_pk_bf16_f32 v7, v14, v15
	ds_write_b128 v38, v[4:7] offset:96
	s_nop 1
	v_lshlrev_b32_e32 v4, 16, v0
	v_and_b32_e32 v5, 0xffff0000, v0
	v_lshlrev_b32_e32 v0, 16, v1
	v_and_b32_e32 v1, 0xffff0000, v1
	v_pk_mul_f32 v[6:7], v[122:123], v[0:1] op_sel_hi:[0,1]
	v_lshlrev_b32_e32 v0, 16, v2
	v_and_b32_e32 v1, 0xffff0000, v2
	v_pk_mul_f32 v[8:9], v[122:123], v[0:1] op_sel_hi:[0,1]
	v_lshlrev_b32_e32 v0, 16, v3
	v_and_b32_e32 v1, 0xffff0000, v3
	v_pk_mul_f32 v[4:5], v[122:123], v[4:5] op_sel_hi:[0,1]
	v_pk_mul_f32 v[10:11], v[122:123], v[0:1] op_sel_hi:[0,1]
	v_cvt_pk_bf16_f32 v0, v4, v5
	v_cvt_pk_bf16_f32 v1, v6, v7
	v_cvt_pk_bf16_f32 v2, v8, v9
	v_cvt_pk_bf16_f32 v3, v10, v11
	ds_write_b128 v38, v[0:3] offset:112
	v_readfirstlane_b32 s64, v32
	v_readfirstlane_b32 s65, v33
	v_mbcnt_lo_u32_b32 v34, -1, 0
	v_mbcnt_hi_u32_b32 v34, -1, v34
	v_and_b32_e32 v35, 56, v34
	v_mul_u32_u24_e32 v35, 0x90, v35
	v_and_b32_e32 v36, 7, v34
	v_lshl_add_u32 v35, v36, 4, v35
	v_add_u32_e32 v35, s57, v35
	v_lshlrev_b32_e32 v37, 4, v34
	ds_read_b128 v[50:53], v35
	ds_read_b128 v[54:57], v35 offset:144
	ds_read_b128 v[58:61], v35 offset:288
	ds_read_b128 v[62:65], v35 offset:432
	s_waitcnt lgkmcnt(0)
	global_store_dwordx4 v37, v[50:53], s[64:65]
	s_add_u32 s64, s64, 0x100000
	s_addc_u32 s65, s65, 0
	global_store_dwordx4 v37, v[54:57], s[64:65]
	s_add_u32 s64, s64, 0x100000
	s_addc_u32 s65, s65, 0
	global_store_dwordx4 v37, v[58:61], s[64:65]
	s_add_u32 s64, s64, 0x100000
	s_addc_u32 s65, s65, 0
	global_store_dwordx4 v37, v[62:65], s[64:65]
	s_add_u32 s64, s64, 0x100000
	s_addc_u32 s65, s65, 0
	ds_read_b128 v[50:53], v35 offset:576
	ds_read_b128 v[54:57], v35 offset:720
	ds_read_b128 v[58:61], v35 offset:864
	ds_read_b128 v[62:65], v35 offset:1008
	s_waitcnt lgkmcnt(0)
	global_store_dwordx4 v37, v[50:53], s[64:65]
	s_add_u32 s64, s64, 0x100000
	s_addc_u32 s65, s65, 0
	global_store_dwordx4 v37, v[54:57], s[64:65]
	s_add_u32 s64, s64, 0x100000
	s_addc_u32 s65, s65, 0
	global_store_dwordx4 v37, v[58:61], s[64:65]
	s_add_u32 s64, s64, 0x100000
	s_addc_u32 s65, s65, 0
	global_store_dwordx4 v37, v[62:65], s[64:65]
	s_add_u32 s64, s64, 0x100000
	s_addc_u32 s65, s65, 0
	s_cmpk_lt_i32 s40, 0x100
	s_cbranch_scc1 .LBB0_535
